# v27: + DPP (same pairing) for the 16-lane score reductions in the sample-side NSA unit and for the prompt top-k max reduction
# speedup vs baseline: 1.0374x; 1.0072x over previous
.LBB0_2752:
	s_lshr_b32 s10, s52, 2
	s_cmp_lt_u32 s52, 4
	s_cselect_b64 vcc, -1, 0
	s_cmp_eq_u32 s10, 2
	s_cselect_b32 s12, s31, s29
	s_cselect_b32 s13, s48, s30
	s_cmp_eq_u32 s10, 1
	s_cselect_b64 s[10:11], -1, 0
	v_cndmask_b32_e64 v66, v106, v108, s[10:11]
	v_cndmask_b32_e64 v67, v107, v109, s[10:11]
	s_and_b64 s[10:11], s[10:11], exec
	s_cselect_b32 s14, s27, s28
	s_and_b64 s[10:11], vcc, exec
	s_cselect_b32 s14, s26, s14
	s_sub_i32 s10, s49, 32
	s_and_b32 s15, s10, 32
	s_or_b32 s10, s15, s14
	v_add_u32_e32 v80, s10, v100
	v_add_u32_e32 v144, 16, v80
	v_cndmask_b32_e32 v78, v66, v104, vcc
	v_subrev_u32_e32 v66, s14, v144
	v_cndmask_b32_e32 v79, v67, v105, vcc
	v_ashrrev_i32_e32 v67, 31, v66
	v_lshlrev_b64 v[66:67], 10, v[66:67]
	v_lshl_add_u64 v[66:67], v[78:79], 0, v[66:67]
	v_mov_b32_e32 v82, s13
	v_cmp_gt_i32_e64 s[10:11], s44, v144
	v_mov_b32_e32 v83, s12
	v_add_u32_e32 v147, 20, v80
	v_cndmask_b32_e64 v67, v82, v67, s[10:11]
	v_cndmask_b32_e64 v66, v83, v66, s[10:11]
	v_lshl_add_u64 v[66:67], v[66:67], 0, v[98:99]
	v_add_u32_e32 v146, 24, v80
	v_add_u32_e32 v145, 28, v80
	global_load_dwordx4 v[94:97], v[66:67], off
	global_load_dwordx4 v[74:77], v[66:67], off offset:512
	v_subrev_u32_e32 v66, s14, v147
	v_subrev_u32_e32 v70, s14, v146
	v_subrev_u32_e32 v80, s14, v145
	v_ashrrev_i32_e32 v67, 31, v66
	v_ashrrev_i32_e32 v71, 31, v70
	v_ashrrev_i32_e32 v81, 31, v80
	v_lshlrev_b64 v[66:67], 10, v[66:67]
	v_lshlrev_b64 v[70:71], 10, v[70:71]
	v_lshlrev_b64 v[80:81], 10, v[80:81]
	v_lshl_add_u64 v[66:67], v[78:79], 0, v[66:67]
	v_lshl_add_u64 v[70:71], v[78:79], 0, v[70:71]
	v_lshl_add_u64 v[78:79], v[78:79], 0, v[80:81]
	s_waitcnt vmcnt(0) lgkmcnt(0)
	v_mul_f32_e32 v80, v11, v3
	v_fmac_f32_e32 v80, v10, v2
	v_fmac_f32_e32 v80, v12, v4
	v_fmac_f32_e32 v80, v13, v5
	v_cmp_gt_i32_e64 s[10:11], s44, v147
	v_mul_f32_e32 v148, v11, v27
	v_fmac_f32_e32 v148, v10, v26
	v_cndmask_b32_e64 v67, v82, v67, s[10:11]
	s_waitcnt lgkmcnt(0)
	v_add_f32_dpp v80, v80, v80 quad_perm:[1,0,3,2] row_mask:0xf bank_mask:0xf
	v_cndmask_b32_e64 v66, v83, v66, s[10:11]
	v_cmp_gt_i32_e64 s[10:11], s44, v146
	v_mul_f32_e32 v125, v23, v3
	v_cndmask_b32_e64 v71, v82, v71, s[10:11]
	v_cndmask_b32_e64 v70, v83, v70, s[10:11]
	v_cmp_gt_i32_e64 s[10:11], s44, v145
	s_waitcnt lgkmcnt(0)
	v_add_f32_dpp v80, v80, v80 quad_perm:[2,3,0,1] row_mask:0xf bank_mask:0xf
	v_cndmask_b32_e64 v79, v82, v79, s[10:11]
	v_mul_f32_e32 v82, v15, v3
	v_fmac_f32_e32 v82, v14, v2
	v_fmac_f32_e32 v82, v16, v4
	v_fmac_f32_e32 v82, v17, v5
	v_cndmask_b32_e64 v78, v83, v78, s[10:11]
	s_and_b32 s10, s52, 12
	s_waitcnt lgkmcnt(0)
	v_add_f32_dpp v118, v80, v80 row_half_mirror row_mask:0xf bank_mask:0xf
	s_cmp_eq_u32 s10, 4
	s_waitcnt lgkmcnt(0)
	v_add_f32_dpp v120, v82, v82 quad_perm:[1,0,3,2] row_mask:0xf bank_mask:0xf
	s_cselect_b32 s12, s27, s28
	s_and_b64 s[10:11], vcc, exec
	s_cselect_b32 s10, s26, s12
	s_or_b32 s10, s10, s15
	v_add_u32_e32 v156, s10, v100
	v_sub_u32_e32 v84, 0x800, v156
	s_waitcnt lgkmcnt(0)
	v_add_f32_dpp v118, v118, v118 row_mirror row_mask:0xf bank_mask:0xf
	s_waitcnt lgkmcnt(0)
	v_add_f32_dpp v119, v120, v120 quad_perm:[2,3,0,1] row_mask:0xf bank_mask:0xf
	v_cvt_f32_u32_e32 v124, v84
	v_cmp_gt_i32_e32 vcc, s45, v156
	v_fmac_f32_e32 v125, v22, v2
	v_fma_f32 v118, -v127, v124, v118
	v_cndmask_b32_e32 v169, v135, v118, vcc
	s_waitcnt lgkmcnt(0)
	v_add_f32_dpp v120, v119, v119 row_half_mirror row_mask:0xf bank_mask:0xf
	v_pk_mul_f32 v[118:119], v[12:13], v[28:29]
	v_fmac_f32_e32 v125, v24, v4
	v_add_f32_e32 v118, v118, v148
	v_add_f32_e32 v118, v119, v118
	v_fmac_f32_e32 v125, v25, v5
	v_mul_f32_e32 v150, v15, v27
	v_fmac_f32_e32 v150, v14, v26
	s_waitcnt lgkmcnt(0)
	v_add_f32_dpp v118, v118, v118 quad_perm:[1,0,3,2] row_mask:0xf bank_mask:0xf
	v_fmac_f32_e32 v150, v16, v28
	s_waitcnt lgkmcnt(0)
	v_add_f32_dpp v125, v125, v125 quad_perm:[1,0,3,2] row_mask:0xf bank_mask:0xf
	v_fmac_f32_e32 v150, v17, v29
	ds_bpermute_b32 v148, v139, v125
	s_waitcnt lgkmcnt(0)
	v_add_f32_dpp v118, v118, v118 quad_perm:[2,3,0,1] row_mask:0xf bank_mask:0xf
	s_movk_i32 s10, 0x7fd
	s_waitcnt lgkmcnt(0)
	v_add_f32_e32 v148, v125, v148
	v_sub_u32_e32 v125, 0x7fc, v156
	s_waitcnt lgkmcnt(0)
	v_add_f32_dpp v118, v118, v118 row_half_mirror row_mask:0xf bank_mask:0xf
	v_cvt_f32_u32_e32 v125, v125
	v_cmp_gt_i32_e64 s[10:11], s10, v156
	v_mul_f32_e32 v154, v11, v35
	v_fmac_f32_e32 v154, v10, v34
	s_waitcnt lgkmcnt(0)
	v_add_f32_dpp v118, v118, v118 row_mirror row_mask:0xf bank_mask:0xf
	v_add_f32_dpp v119, v150, v150 quad_perm:[1,0,3,2] row_mask:0xf bank_mask:0xf
	v_mul_f32_e32 v151, v19, v27
	v_fma_f32 v118, -v127, v125, v118
	v_fmac_f32_e32 v151, v18, v26
	v_fmac_f32_e32 v151, v20, v28
	v_cndmask_b32_e64 v172, v135, v118, s[10:11]
	s_waitcnt lgkmcnt(0)
	v_add_f32_dpp v118, v119, v119 quad_perm:[2,3,0,1] row_mask:0xf bank_mask:0xf
	v_fmac_f32_e32 v151, v21, v29
	v_lshl_add_u64 v[66:67], v[66:67], 0, v[98:99]
	v_lshl_add_u64 v[70:71], v[70:71], 0, v[98:99]
	v_lshl_add_u64 v[78:79], v[78:79], 0, v[98:99]
	s_waitcnt lgkmcnt(0)
	v_add_f32_dpp v164, v118, v118 row_half_mirror row_mask:0xf bank_mask:0xf
	v_pk_mul_f32 v[118:119], v[12:13], v[36:37]
	s_waitcnt lgkmcnt(0)
	v_add_f32_dpp v150, v151, v151 quad_perm:[1,0,3,2] row_mask:0xf bank_mask:0xf
	v_mul_f32_e32 v152, v23, v27
	v_add_f32_e32 v118, v118, v154
	v_fmac_f32_e32 v152, v22, v26
	v_add_f32_e32 v118, v119, v118
	v_fmac_f32_e32 v152, v24, v28
	v_fmac_f32_e32 v152, v25, v29
	global_load_dwordx4 v[90:93], v[66:67], off
	s_nop 0
	global_load_dwordx4 v[66:69], v[66:67], off offset:512
	s_waitcnt lgkmcnt(0)
	v_add_f32_dpp v118, v118, v118 quad_perm:[1,0,3,2] row_mask:0xf bank_mask:0xf
	v_add_f32_dpp v152, v152, v152 quad_perm:[1,0,3,2] row_mask:0xf bank_mask:0xf
	global_load_dwordx4 v[86:89], v[70:71], off
	s_nop 0
	global_load_dwordx4 v[70:73], v[70:71], off offset:512
	s_nop 0
	global_load_dwordx4 v[82:85], v[78:79], off
	s_nop 0
	global_load_dwordx4 v[78:81], v[78:79], off offset:512
	v_mul_f32_e32 v154, v15, v35
	s_waitcnt lgkmcnt(0)
	v_add_f32_dpp v118, v118, v118 quad_perm:[2,3,0,1] row_mask:0xf bank_mask:0xf
	v_fmac_f32_e32 v154, v14, v34
	v_fmac_f32_e32 v154, v16, v36
	v_add_f32_dpp v150, v150, v150 quad_perm:[2,3,0,1] row_mask:0xf bank_mask:0xf
	v_add_f32_dpp v152, v152, v152 quad_perm:[2,3,0,1] row_mask:0xf bank_mask:0xf
	v_fmac_f32_e32 v154, v17, v37
	s_waitcnt lgkmcnt(0)
	v_add_f32_dpp v118, v118, v118 row_half_mirror row_mask:0xf bank_mask:0xf
	v_add_f32_dpp v158, v150, v150 row_half_mirror row_mask:0xf bank_mask:0xf
	v_add_f32_dpp v150, v152, v152 row_half_mirror row_mask:0xf bank_mask:0xf
	v_sub_u32_e32 v152, 0x7f8, v156
	v_add_f32_dpp v154, v154, v154 quad_perm:[1,0,3,2] row_mask:0xf bank_mask:0xf
	v_cvt_f32_u32_e32 v152, v152
	v_or_b32_e32 v153, 8, v156
	s_waitcnt lgkmcnt(0)
	v_add_f32_dpp v118, v118, v118 row_mirror row_mask:0xf bank_mask:0xf
	v_fma_f32 v118, -v127, v152, v118
	v_cmp_gt_i32_e64 s[12:13], s45, v153
	v_mul_f32_e32 v153, v19, v35
	v_fmac_f32_e32 v153, v18, v34
	v_cndmask_b32_e64 v173, v135, v118, s[12:13]
	v_add_f32_dpp v118, v154, v154 quad_perm:[2,3,0,1] row_mask:0xf bank_mask:0xf
	v_mul_f32_e32 v155, v23, v35
	v_fmac_f32_e32 v155, v22, v34
	v_fmac_f32_e32 v153, v20, v36
	v_fmac_f32_e32 v155, v24, v36
	v_fmac_f32_e32 v153, v21, v37
	v_fmac_f32_e32 v155, v25, v37
	ds_bpermute_b32 v160, v138, v155
	s_movk_i32 s14, 0x7f5
	v_cmp_gt_i32_e64 s[14:15], s14, v156
	s_waitcnt lgkmcnt(0)
	v_add_f32_dpp v153, v153, v153 quad_perm:[1,0,3,2] row_mask:0xf bank_mask:0xf
	v_add_f32_e32 v160, v155, v160
	v_pk_mul_f32 v[154:155], v[10:11], v[46:47]
	v_add_f32_dpp v167, v118, v118 row_half_mirror row_mask:0xf bank_mask:0xf
	v_pk_mul_f32 v[118:119], v[12:13], v[48:49]
	v_add_f32_e32 v154, v154, v155
	v_add_f32_e32 v118, v118, v154
	v_add_f32_e32 v118, v119, v118
	v_mul_f32_e32 v122, v19, v3
	s_waitcnt lgkmcnt(0)
	v_add_f32_dpp v153, v153, v153 quad_perm:[2,3,0,1] row_mask:0xf bank_mask:0xf
	v_add_f32_dpp v155, v160, v160 quad_perm:[2,3,0,1] row_mask:0xf bank_mask:0xf
	v_add_f32_dpp v118, v118, v118 quad_perm:[1,0,3,2] row_mask:0xf bank_mask:0xf
	v_fmac_f32_e32 v122, v18, v2
	s_waitcnt lgkmcnt(0)
	v_add_f32_dpp v160, v153, v153 row_half_mirror row_mask:0xf bank_mask:0xf
	v_add_f32_dpp v153, v155, v155 row_half_mirror row_mask:0xf bank_mask:0xf
	v_mul_f32_e32 v162, v15, v47
	v_add_f32_dpp v118, v118, v118 quad_perm:[2,3,0,1] row_mask:0xf bank_mask:0xf
	v_fmac_f32_e32 v162, v14, v46
	v_fmac_f32_e32 v162, v16, v48
	v_fmac_f32_e32 v162, v17, v49
	v_sub_u32_e32 v155, 0x7f4, v156
	s_waitcnt lgkmcnt(0)
	v_add_f32_dpp v118, v118, v118 row_half_mirror row_mask:0xf bank_mask:0xf
	v_cvt_f32_u32_e32 v155, v155
	v_add_f32_dpp v162, v162, v162 quad_perm:[1,0,3,2] row_mask:0xf bank_mask:0xf
	v_mul_f32_e32 v156, v19, v47
	s_waitcnt lgkmcnt(0)
	v_add_f32_dpp v118, v118, v118 row_mirror row_mask:0xf bank_mask:0xf
	v_fma_f32 v118, -v127, v155, v118
	v_cndmask_b32_e64 v174, v135, v118, s[14:15]
	v_add_f32_dpp v118, v162, v162 quad_perm:[2,3,0,1] row_mask:0xf bank_mask:0xf
	v_mul_f32_e32 v163, v23, v47
	v_fmac_f32_e32 v156, v18, v46
	v_fmac_f32_e32 v163, v22, v46
	v_fmac_f32_e32 v122, v20, v4
	v_fmac_f32_e32 v156, v20, v48
	v_fmac_f32_e32 v163, v24, v48
	v_fmac_f32_e32 v122, v21, v5
	v_fmac_f32_e32 v156, v21, v49
	v_fmac_f32_e32 v163, v25, v49
	v_max3_f32 v157, v169, s35, v172
	s_waitcnt lgkmcnt(0)
	v_add_f32_dpp v122, v122, v122 quad_perm:[1,0,3,2] row_mask:0xf bank_mask:0xf
	v_add_f32_dpp v170, v118, v118 row_half_mirror row_mask:0xf bank_mask:0xf
	v_add_f32_dpp v118, v156, v156 quad_perm:[1,0,3,2] row_mask:0xf bank_mask:0xf
	v_add_f32_dpp v156, v163, v163 quad_perm:[1,0,3,2] row_mask:0xf bank_mask:0xf
	v_max3_f32 v157, v157, v173, v174
	ds_bpermute_b32 v163, v142, v157
	s_waitcnt lgkmcnt(0)
	v_add_f32_dpp v122, v122, v122 quad_perm:[2,3,0,1] row_mask:0xf bank_mask:0xf
	v_add_f32_dpp v118, v118, v118 quad_perm:[2,3,0,1] row_mask:0xf bank_mask:0xf
	v_add_f32_dpp v156, v156, v156 quad_perm:[2,3,0,1] row_mask:0xf bank_mask:0xf
	v_max_f32_e32 v162, v163, v163
	v_max_f32_e32 v176, v157, v162
	ds_bpermute_b32 v177, v143, v176
	s_waitcnt lgkmcnt(0)
	v_add_f32_dpp v122, v122, v122 row_half_mirror row_mask:0xf bank_mask:0xf
	v_add_f32_dpp v148, v148, v148 row_half_mirror row_mask:0xf bank_mask:0xf
	v_add_f32_dpp v162, v118, v118 row_half_mirror row_mask:0xf bank_mask:0xf
	v_add_f32_dpp v156, v156, v156 row_half_mirror row_mask:0xf bank_mask:0xf
	ds_bpermute_b32 v121, v141, v120
	ds_bpermute_b32 v123, v141, v122
	ds_bpermute_b32 v149, v141, v148
	ds_bpermute_b32 v165, v141, v164
	ds_bpermute_b32 v159, v141, v158
	ds_bpermute_b32 v151, v141, v150
	ds_bpermute_b32 v168, v141, v167
	ds_bpermute_b32 v161, v141, v160
	ds_bpermute_b32 v154, v141, v153
	ds_bpermute_b32 v171, v141, v170
	ds_bpermute_b32 v163, v141, v162
	ds_bpermute_b32 v157, v141, v156
	v_max_f32_e32 v118, v177, v177
	v_max_f32_e32 v175, v176, v118
	v_cmp_neq_f32_e64 s[16:17], s35, v175
	v_mov_b64_e32 v[118:119], v[112:113]
	s_and_saveexec_b64 s[22:23], s[16:17]
	s_cbranch_execz .LBB0_2754
	v_max_f32_e32 v118, v175, v175
	v_max_f32_e32 v119, v113, v113
	v_max_f32_e32 v119, v119, v118
	v_sub_f32_e32 v118, v169, v119
	v_mul_f32_e32 v118, 0x3fb8aa3b, v118
	v_exp_f32_e32 v118, v118
	v_sub_f32_e32 v113, v113, v119
	v_mul_f32_e32 v113, 0x3fb8aa3b, v113
	v_add_f32_e32 v169, 0, v118
	v_pk_fma_f32 v[176:177], v[8:9], v[118:119], 0 op_sel_hi:[1,0,0]
	v_pk_fma_f32 v[178:179], v[6:7], v[118:119], 0 op_sel_hi:[1,0,0]
	v_sub_f32_e32 v118, v172, v119
	v_mul_f32_e32 v118, 0x3fb8aa3b, v118
	v_exp_f32_e32 v118, v118
	s_nop 0
	v_add_f32_e32 v169, v118, v169
	v_pk_fma_f32 v[176:177], v[32:33], v[118:119], v[176:177] op_sel_hi:[1,0,1]
	v_pk_fma_f32 v[178:179], v[30:31], v[118:119], v[178:179] op_sel_hi:[1,0,1]
	v_sub_f32_e32 v118, v173, v119
	v_mul_f32_e32 v118, 0x3fb8aa3b, v118
	v_exp_f32_e32 v118, v118
	s_nop 0
	v_add_f32_e32 v169, v118, v169
	v_pk_fma_f32 v[172:173], v[38:39], v[118:119], v[178:179] op_sel_hi:[1,0,1]
	v_pk_fma_f32 v[176:177], v[40:41], v[118:119], v[176:177] op_sel_hi:[1,0,1]
	v_sub_f32_e32 v118, v174, v119
	v_mul_f32_e32 v118, 0x3fb8aa3b, v118
	v_exp_f32_e32 v118, v118
	s_nop 0
	v_add_f32_e32 v169, v118, v169
	v_pk_fma_f32 v[174:175], v[56:57], v[118:119], v[176:177] op_sel_hi:[1,0,1]
	v_exp_f32_e32 v176, v113
	ds_bpermute_b32 v113, v142, v169
	v_pk_fma_f32 v[172:173], v[54:55], v[118:119], v[172:173] op_sel_hi:[1,0,1]
	ds_bpermute_b32 v178, v142, v174
	ds_bpermute_b32 v179, v142, v175
	s_waitcnt lgkmcnt(0)
	v_add_f32_e32 v113, v169, v113
	ds_bpermute_b32 v118, v143, v113
	v_pk_add_f32 v[174:175], v[174:175], v[178:179]
	ds_bpermute_b32 v178, v143, v174
	ds_bpermute_b32 v179, v143, v175
	s_waitcnt lgkmcnt(0)
	v_add_f32_e32 v118, v113, v118
	v_fmac_f32_e32 v118, v112, v176
	ds_bpermute_b32 v112, v142, v172
	ds_bpermute_b32 v113, v142, v173
	s_waitcnt lgkmcnt(0)
	v_pk_add_f32 v[112:113], v[172:173], v[112:113]
	ds_bpermute_b32 v172, v143, v112
	ds_bpermute_b32 v173, v143, v113
	s_waitcnt lgkmcnt(0)
	v_pk_add_f32 v[112:113], v[112:113], v[172:173]
	v_pk_add_f32 v[172:173], v[174:175], v[178:179]
	v_pk_fma_f32 v[62:63], v[62:63], v[176:177], v[112:113] op_sel_hi:[1,0,1]
	v_pk_fma_f32 v[64:65], v[64:65], v[176:177], v[172:173] op_sel_hi:[1,0,1]
	v_mov_b32_e32 v112, v118
	v_mov_b32_e32 v113, v119

.LBB0_2762:
	v_mul_f32_e32 v149, v11, v95
	v_fmac_f32_e32 v149, v10, v94
	v_fmac_f32_e32 v149, v12, v96
	v_fmac_f32_e32 v149, v13, v97
	v_sub_u32_e32 v148, 0x800, v144
	v_cvt_f32_u32_e32 v148, v148
	v_cmp_gt_i32_e32 vcc, s45, v144
	s_waitcnt vmcnt(0)
	v_pk_mul_f32 v[154:155], v[12:13], v[92:93]
	s_waitcnt lgkmcnt(0)
	v_add_f32_dpp v149, v149, v149 quad_perm:[1,0,3,2] row_mask:0xf bank_mask:0xf
	v_cmp_gt_i32_e64 s[10:11], s45, v147
	v_pk_mul_f32 v[158:159], v[12:13], v[88:89]
	v_cmp_gt_i32_e64 s[12:13], s45, v146
	v_pk_mul_f32 v[160:161], v[10:11], v[82:83]
	s_waitcnt lgkmcnt(0)
	v_add_f32_dpp v149, v149, v149 quad_perm:[2,3,0,1] row_mask:0xf bank_mask:0xf
	v_cmp_gt_i32_e64 s[14:15], s45, v145
	s_waitcnt lgkmcnt(0)
	v_add_f32_dpp v149, v149, v149 row_half_mirror row_mask:0xf bank_mask:0xf
	s_waitcnt lgkmcnt(0)
	s_nop 0
	v_add_f32_dpp v149, v149, v149 row_mirror row_mask:0xf bank_mask:0xf
	v_fma_f32 v149, -v127, v148, v149
	v_cndmask_b32_e32 v153, v135, v149, vcc
	v_mul_f32_e32 v149, v15, v95
	v_fmac_f32_e32 v149, v14, v94
	v_fmac_f32_e32 v149, v16, v96
	v_fmac_f32_e32 v149, v17, v97
	s_waitcnt lgkmcnt(0)
	s_nop 0
	v_add_f32_dpp v149, v149, v149 quad_perm:[1,0,3,2] row_mask:0xf bank_mask:0xf
	s_waitcnt lgkmcnt(0)
	s_nop 0
	v_add_f32_dpp v149, v149, v149 quad_perm:[2,3,0,1] row_mask:0xf bank_mask:0xf
	s_waitcnt lgkmcnt(0)
	s_nop 0
	v_add_f32_dpp v151, v149, v149 row_half_mirror row_mask:0xf bank_mask:0xf
	v_mul_f32_e32 v149, v19, v95
	v_mul_f32_e32 v95, v23, v95
	v_fmac_f32_e32 v149, v18, v94
	v_fmac_f32_e32 v95, v22, v94
	v_fmac_f32_e32 v149, v20, v96
	v_fmac_f32_e32 v95, v24, v96
	v_fmac_f32_e32 v149, v21, v97
	v_fmac_f32_e32 v95, v25, v97
	v_mul_f32_e32 v97, v11, v91
	v_fmac_f32_e32 v97, v10, v90
	v_add_f32_e32 v97, v154, v97
	v_add_f32_e32 v97, v155, v97
	ds_bpermute_b32 v94, v138, v95
	ds_bpermute_b32 v152, v141, v151
	s_waitcnt lgkmcnt(0)
	v_add_f32_dpp v97, v97, v97 quad_perm:[1,0,3,2] row_mask:0xf bank_mask:0xf
	s_waitcnt lgkmcnt(0)
	v_add_f32_e32 v94, v95, v94
	s_waitcnt lgkmcnt(0)
	v_add_f32_dpp v149, v149, v149 quad_perm:[1,0,3,2] row_mask:0xf bank_mask:0xf
	s_waitcnt lgkmcnt(0)
	v_add_f32_dpp v97, v97, v97 quad_perm:[2,3,0,1] row_mask:0xf bank_mask:0xf
	s_waitcnt lgkmcnt(0)
	v_add_f32_dpp v94, v94, v94 quad_perm:[2,3,0,1] row_mask:0xf bank_mask:0xf
	s_waitcnt lgkmcnt(0)
	v_add_f32_dpp v149, v149, v149 quad_perm:[2,3,0,1] row_mask:0xf bank_mask:0xf
	s_waitcnt lgkmcnt(0)
	v_add_f32_dpp v97, v97, v97 row_half_mirror row_mask:0xf bank_mask:0xf
	s_waitcnt lgkmcnt(0)
	v_add_f32_dpp v94, v94, v94 row_half_mirror row_mask:0xf bank_mask:0xf
	v_sub_u32_e32 v95, 0x7fc, v144
	v_cvt_f32_u32_e32 v95, v95
	s_waitcnt lgkmcnt(0)
	v_add_f32_dpp v149, v149, v149 row_half_mirror row_mask:0xf bank_mask:0xf
	s_waitcnt lgkmcnt(0)
	v_add_f32_dpp v97, v97, v97 row_mirror row_mask:0xf bank_mask:0xf
	ds_bpermute_b32 v150, v141, v149
	v_fma_f32 v97, -v127, v95, v97
	v_cndmask_b32_e64 v156, v135, v97, s[10:11]
	v_mul_f32_e32 v97, v15, v91
	v_fmac_f32_e32 v97, v14, v90
	v_fmac_f32_e32 v97, v16, v92
	v_fmac_f32_e32 v97, v17, v93
	v_max3_f32 v162, v153, s35, v156
	ds_bpermute_b32 v96, v141, v94
	s_waitcnt lgkmcnt(0)
	v_add_f32_dpp v97, v97, v97 quad_perm:[1,0,3,2] row_mask:0xf bank_mask:0xf
	s_waitcnt lgkmcnt(0)
	s_nop 0
	v_add_f32_dpp v97, v97, v97 quad_perm:[2,3,0,1] row_mask:0xf bank_mask:0xf
	s_waitcnt lgkmcnt(0)
	s_nop 0
	v_add_f32_dpp v154, v97, v97 row_half_mirror row_mask:0xf bank_mask:0xf
	v_mul_f32_e32 v97, v19, v91
	v_mul_f32_e32 v91, v23, v91
	v_fmac_f32_e32 v97, v18, v90
	v_fmac_f32_e32 v91, v22, v90
	v_fmac_f32_e32 v97, v20, v92
	v_fmac_f32_e32 v91, v24, v92
	v_fmac_f32_e32 v97, v21, v93
	v_fmac_f32_e32 v91, v25, v93
	v_mul_f32_e32 v93, v11, v87
	v_fmac_f32_e32 v93, v10, v86
	v_add_f32_e32 v93, v158, v93
	v_add_f32_e32 v93, v159, v93
	ds_bpermute_b32 v90, v138, v91
	ds_bpermute_b32 v155, v141, v154
	s_waitcnt lgkmcnt(0)
	v_add_f32_dpp v93, v93, v93 quad_perm:[1,0,3,2] row_mask:0xf bank_mask:0xf
	s_waitcnt lgkmcnt(0)
	v_add_f32_e32 v90, v91, v90
	s_waitcnt lgkmcnt(0)
	v_add_f32_dpp v97, v97, v97 quad_perm:[1,0,3,2] row_mask:0xf bank_mask:0xf
	s_waitcnt lgkmcnt(0)
	v_add_f32_dpp v93, v93, v93 quad_perm:[2,3,0,1] row_mask:0xf bank_mask:0xf
	s_waitcnt lgkmcnt(0)
	v_add_f32_dpp v90, v90, v90 quad_perm:[2,3,0,1] row_mask:0xf bank_mask:0xf
	ds_bpermute_b32 v91, v140, v90
	s_waitcnt lgkmcnt(0)
	v_add_f32_dpp v97, v97, v97 quad_perm:[2,3,0,1] row_mask:0xf bank_mask:0xf
	s_waitcnt lgkmcnt(0)
	v_add_f32_dpp v93, v93, v93 row_half_mirror row_mask:0xf bank_mask:0xf
	s_waitcnt lgkmcnt(0)
	v_add_f32_e32 v91, v90, v91
	v_sub_u32_e32 v90, 0x7f8, v144
	v_cvt_f32_u32_e32 v90, v90
	s_waitcnt lgkmcnt(0)
	v_add_f32_dpp v97, v97, v97 row_half_mirror row_mask:0xf bank_mask:0xf
	s_waitcnt lgkmcnt(0)
	v_add_f32_dpp v93, v93, v93 row_mirror row_mask:0xf bank_mask:0xf
	ds_bpermute_b32 v147, v141, v97
	v_fma_f32 v93, -v127, v90, v93
	v_cndmask_b32_e64 v159, v135, v93, s[12:13]
	v_mul_f32_e32 v93, v15, v87
	v_fmac_f32_e32 v93, v14, v86
	v_fmac_f32_e32 v93, v16, v88
	v_fmac_f32_e32 v93, v17, v89
	ds_bpermute_b32 v92, v141, v91
	s_waitcnt lgkmcnt(0)
	v_add_f32_dpp v93, v93, v93 quad_perm:[1,0,3,2] row_mask:0xf bank_mask:0xf
	s_waitcnt lgkmcnt(0)
	s_nop 0
	v_add_f32_dpp v93, v93, v93 quad_perm:[2,3,0,1] row_mask:0xf bank_mask:0xf
	s_waitcnt lgkmcnt(0)
	s_nop 0
	v_add_f32_dpp v157, v93, v93 row_half_mirror row_mask:0xf bank_mask:0xf
	v_mul_f32_e32 v93, v19, v87
	v_mul_f32_e32 v87, v23, v87
	v_fmac_f32_e32 v87, v22, v86
	v_fmac_f32_e32 v87, v24, v88
	v_fmac_f32_e32 v87, v25, v89
	v_fmac_f32_e32 v93, v18, v86
	ds_bpermute_b32 v86, v138, v87
	v_fmac_f32_e32 v93, v20, v88
	v_fmac_f32_e32 v93, v21, v89
	v_add_f32_e32 v89, v160, v161
	s_waitcnt lgkmcnt(0)
	v_add_f32_e32 v86, v87, v86
	ds_bpermute_b32 v158, v141, v157
	s_waitcnt lgkmcnt(0)
	v_add_f32_dpp v93, v93, v93 quad_perm:[1,0,3,2] row_mask:0xf bank_mask:0xf
	s_waitcnt lgkmcnt(0)
	v_add_f32_dpp v86, v86, v86 quad_perm:[2,3,0,1] row_mask:0xf bank_mask:0xf
	s_waitcnt lgkmcnt(0)
	v_add_f32_dpp v93, v93, v93 quad_perm:[2,3,0,1] row_mask:0xf bank_mask:0xf
	s_waitcnt lgkmcnt(0)
	v_add_f32_dpp v86, v86, v86 row_half_mirror row_mask:0xf bank_mask:0xf
	v_sub_u32_e32 v87, 0x7f4, v144
	v_pk_mul_f32 v[144:145], v[12:13], v[84:85]
	v_cvt_f32_u32_e32 v87, v87
	v_add_f32_e32 v89, v144, v89
	v_add_f32_e32 v89, v145, v89
	s_waitcnt lgkmcnt(0)
	v_add_f32_dpp v93, v93, v93 row_half_mirror row_mask:0xf bank_mask:0xf
	ds_bpermute_b32 v146, v141, v93
	ds_bpermute_b32 v88, v141, v86
	s_waitcnt lgkmcnt(0)
	v_add_f32_dpp v89, v89, v89 quad_perm:[1,0,3,2] row_mask:0xf bank_mask:0xf
	s_waitcnt lgkmcnt(0)
	s_nop 0
	v_add_f32_dpp v89, v89, v89 quad_perm:[2,3,0,1] row_mask:0xf bank_mask:0xf
	s_waitcnt lgkmcnt(0)
	s_nop 0
	v_add_f32_dpp v89, v89, v89 row_half_mirror row_mask:0xf bank_mask:0xf
	s_waitcnt lgkmcnt(0)
	s_nop 0
	v_add_f32_dpp v89, v89, v89 row_mirror row_mask:0xf bank_mask:0xf
	v_fma_f32 v89, -v127, v87, v89
	v_cndmask_b32_e64 v161, v135, v89, s[14:15]
	v_mul_f32_e32 v89, v15, v83
	v_fmac_f32_e32 v89, v14, v82
	v_fmac_f32_e32 v89, v16, v84
	v_fmac_f32_e32 v89, v17, v85
	v_max3_f32 v162, v162, v159, v161
	s_waitcnt lgkmcnt(0)
	v_add_f32_dpp v89, v89, v89 quad_perm:[1,0,3,2] row_mask:0xf bank_mask:0xf
	s_waitcnt lgkmcnt(0)
	s_nop 0
	v_add_f32_dpp v89, v89, v89 quad_perm:[2,3,0,1] row_mask:0xf bank_mask:0xf
	s_waitcnt lgkmcnt(0)
	s_nop 0
	v_add_f32_dpp v145, v89, v89 row_half_mirror row_mask:0xf bank_mask:0xf
	v_mul_f32_e32 v89, v19, v83
	v_mul_f32_e32 v83, v23, v83
	v_fmac_f32_e32 v89, v18, v82
	v_fmac_f32_e32 v83, v22, v82
	v_fmac_f32_e32 v89, v20, v84
	v_fmac_f32_e32 v83, v24, v84
	v_fmac_f32_e32 v89, v21, v85
	v_fmac_f32_e32 v83, v25, v85
	ds_bpermute_b32 v82, v138, v83
	ds_bpermute_b32 v84, v142, v162
	ds_bpermute_b32 v160, v141, v145
	s_waitcnt lgkmcnt(0)
	v_add_f32_dpp v89, v89, v89 quad_perm:[1,0,3,2] row_mask:0xf bank_mask:0xf
	s_waitcnt lgkmcnt(0)
	v_add_f32_e32 v82, v83, v82
	s_waitcnt lgkmcnt(0)
	v_max_f32_e32 v84, v84, v84
	v_max_f32_e32 v84, v162, v84
	ds_bpermute_b32 v85, v143, v84
	s_waitcnt lgkmcnt(0)
	v_add_f32_dpp v89, v89, v89 quad_perm:[2,3,0,1] row_mask:0xf bank_mask:0xf
	s_waitcnt lgkmcnt(0)
	v_add_f32_dpp v82, v82, v82 quad_perm:[2,3,0,1] row_mask:0xf bank_mask:0xf
	s_waitcnt lgkmcnt(0)
	v_max_f32_e32 v85, v85, v85
	v_max_f32_e32 v84, v84, v85
	v_cmp_neq_f32_e64 s[16:17], s35, v84
	s_waitcnt lgkmcnt(0)
	v_add_f32_dpp v89, v89, v89 row_half_mirror row_mask:0xf bank_mask:0xf
	s_waitcnt lgkmcnt(0)
	v_add_f32_dpp v82, v82, v82 row_half_mirror row_mask:0xf bank_mask:0xf
	ds_bpermute_b32 v144, v141, v89
	ds_bpermute_b32 v83, v141, v82
	s_and_saveexec_b64 s[24:25], s[16:17]
	s_cbranch_execz .LBB0_2764
	v_max_f32_e32 v84, v84, v84
	v_max_f32_e32 v85, v113, v113
	v_max_f32_e32 v119, v85, v84
	v_sub_f32_e32 v84, v113, v119
	v_mul_f32_e32 v113, 0x3fb8aa3b, v84
	v_sub_f32_e32 v84, v153, v119
	v_mul_f32_e32 v84, 0x3fb8aa3b, v84
	v_sub_f32_e32 v118, v156, v119
	v_exp_f32_e32 v84, v84
	v_mul_f32_e32 v118, 0x3fb8aa3b, v118
	v_exp_f32_e32 v118, v118
	v_exp_f32_e32 v156, v113
	v_add_f32_e32 v153, 0, v84
	v_pk_fma_f32 v[162:163], v[76:77], v[84:85], 0 op_sel_hi:[1,0,0]
	v_pk_fma_f32 v[84:85], v[74:75], v[84:85], 0 op_sel_hi:[1,0,0]
	v_add_f32_e32 v153, v118, v153
	v_pk_fma_f32 v[162:163], v[68:69], v[118:119], v[162:163] op_sel_hi:[1,0,1]
	v_pk_fma_f32 v[84:85], v[66:67], v[118:119], v[84:85] op_sel_hi:[1,0,1]
	v_sub_f32_e32 v118, v159, v119
	v_mul_f32_e32 v118, 0x3fb8aa3b, v118
	v_exp_f32_e32 v118, v118
	s_nop 0
	v_add_f32_e32 v153, v118, v153
	v_pk_fma_f32 v[84:85], v[70:71], v[118:119], v[84:85] op_sel_hi:[1,0,1]
	v_pk_fma_f32 v[162:163], v[72:73], v[118:119], v[162:163] op_sel_hi:[1,0,1]
	v_sub_f32_e32 v118, v161, v119
	v_mul_f32_e32 v118, 0x3fb8aa3b, v118
	v_exp_f32_e32 v118, v118
	s_nop 0
	v_add_f32_e32 v153, v118, v153
	ds_bpermute_b32 v113, v142, v153
	v_pk_fma_f32 v[162:163], v[80:81], v[118:119], v[162:163] op_sel_hi:[1,0,1]
	v_pk_fma_f32 v[84:85], v[78:79], v[118:119], v[84:85] op_sel_hi:[1,0,1]
	ds_bpermute_b32 v164, v142, v162
	ds_bpermute_b32 v165, v142, v163
	s_waitcnt lgkmcnt(0)
	v_add_f32_e32 v113, v153, v113
	ds_bpermute_b32 v118, v143, v113
	s_waitcnt lgkmcnt(0)
	v_pk_add_f32 v[162:163], v[162:163], v[164:165]
	ds_bpermute_b32 v164, v143, v162
	s_waitcnt lgkmcnt(0)
	v_add_f32_e32 v118, v113, v118
	v_fmac_f32_e32 v118, v112, v156
	ds_bpermute_b32 v112, v142, v84
	ds_bpermute_b32 v113, v142, v85
	ds_bpermute_b32 v165, v143, v163
	s_waitcnt lgkmcnt(0)
	v_pk_add_f32 v[84:85], v[84:85], v[112:113]
	ds_bpermute_b32 v112, v143, v84
	ds_bpermute_b32 v113, v143, v85
	s_waitcnt lgkmcnt(0)
	v_pk_add_f32 v[84:85], v[84:85], v[112:113]
	v_pk_add_f32 v[112:113], v[162:163], v[164:165]
	v_pk_fma_f32 v[62:63], v[62:63], v[156:157], v[84:85] op_sel_hi:[1,0,1]
	v_pk_fma_f32 v[64:65], v[64:65], v[156:157], v[112:113] op_sel_hi:[1,0,1]
	v_mov_b32_e32 v112, v118
	v_mov_b32_e32 v113, v119
.LBB0_2764:
	s_or_b64 exec, exec, s[24:25]
	v_add_f32_e32 v84, v151, v152
	v_fma_f32 v84, -v128, v148, v84
	v_cndmask_b32_e32 v152, v135, v84, vcc
	v_add_f32_e32 v84, v154, v155
	v_fma_f32 v84, -v128, v95, v84
	v_cndmask_b32_e64 v151, v135, v84, s[10:11]
	v_add_f32_e32 v84, v157, v158
	v_fma_f32 v84, -v128, v90, v84
	v_cndmask_b32_e64 v85, v135, v84, s[12:13]
	v_add_f32_e32 v84, v145, v160
	v_fma_f32 v84, -v128, v87, v84
	v_max3_f32 v153, v152, s35, v151
	v_cndmask_b32_e64 v84, v135, v84, s[14:15]
	v_max3_f32 v145, v153, v85, v84
	ds_bpermute_b32 v153, v142, v145
	s_waitcnt lgkmcnt(0)
	v_max_f32_e32 v153, v153, v153
	v_max_f32_e32 v145, v145, v153
	ds_bpermute_b32 v153, v143, v145
	s_waitcnt lgkmcnt(0)
	v_max_f32_e32 v153, v153, v153
	v_max_f32_e32 v145, v145, v153
	v_cmp_neq_f32_e64 s[16:17], s35, v145
	s_and_saveexec_b64 s[24:25], s[16:17]
	s_cbranch_execz .LBB0_2766
	v_max_f32_e32 v120, v145, v145
	v_max_f32_e32 v121, v117, v117
	v_max_f32_e32 v121, v121, v120
	v_sub_f32_e32 v120, v152, v121
	v_mul_f32_e32 v120, 0x3fb8aa3b, v120
	v_exp_f32_e32 v120, v120
	v_sub_f32_e32 v85, v85, v121
	v_mul_f32_e32 v85, 0x3fb8aa3b, v85
	v_sub_f32_e32 v84, v84, v121
	v_add_f32_e32 v145, 0, v120
	v_pk_fma_f32 v[152:153], v[76:77], v[120:121], 0 op_sel_hi:[1,0,0]
	v_pk_fma_f32 v[154:155], v[74:75], v[120:121], 0 op_sel_hi:[1,0,0]
	v_sub_f32_e32 v120, v151, v121
	v_mul_f32_e32 v120, 0x3fb8aa3b, v120
	v_exp_f32_e32 v120, v120
	v_mul_f32_e32 v84, 0x3fb8aa3b, v84
	v_exp_f32_e32 v84, v84
	v_sub_f32_e32 v117, v117, v121
	v_add_f32_e32 v145, v120, v145
	v_pk_fma_f32 v[152:153], v[68:69], v[120:121], v[152:153] op_sel_hi:[1,0,1]
	v_pk_fma_f32 v[154:155], v[66:67], v[120:121], v[154:155] op_sel_hi:[1,0,1]
	v_exp_f32_e32 v120, v85
	v_mul_f32_e32 v117, 0x3fb8aa3b, v117
	v_add_f32_e32 v85, v120, v145
	v_pk_fma_f32 v[154:155], v[70:71], v[120:121], v[154:155] op_sel_hi:[1,0,1]
	v_pk_fma_f32 v[152:153], v[72:73], v[120:121], v[152:153] op_sel_hi:[1,0,1]
	v_add_f32_e32 v120, v84, v85
	v_pk_fma_f32 v[152:153], v[80:81], v[84:85], v[152:153] op_sel_hi:[1,0,1]
	v_pk_fma_f32 v[84:85], v[78:79], v[84:85], v[154:155] op_sel_hi:[1,0,1]
	v_exp_f32_e32 v154, v117
	ds_bpermute_b32 v117, v142, v120
	ds_bpermute_b32 v156, v142, v152
	ds_bpermute_b32 v157, v142, v153
	s_waitcnt lgkmcnt(0)
	v_add_f32_e32 v117, v120, v117
	ds_bpermute_b32 v120, v143, v117
	s_waitcnt lgkmcnt(0)
	v_pk_add_f32 v[152:153], v[152:153], v[156:157]
	ds_bpermute_b32 v156, v143, v152
	ds_bpermute_b32 v157, v143, v153
	s_waitcnt lgkmcnt(0)
	v_add_f32_e32 v120, v117, v120
	v_fmac_f32_e32 v120, v116, v154
	ds_bpermute_b32 v116, v142, v84
	ds_bpermute_b32 v117, v142, v85
	s_waitcnt lgkmcnt(0)
	v_pk_add_f32 v[84:85], v[84:85], v[116:117]
	ds_bpermute_b32 v116, v143, v84
	ds_bpermute_b32 v117, v143, v85
	s_waitcnt lgkmcnt(0)
	v_pk_add_f32 v[84:85], v[84:85], v[116:117]
	v_pk_add_f32 v[116:117], v[152:153], v[156:157]
	v_pk_fma_f32 v[58:59], v[58:59], v[154:155], v[84:85] op_sel_hi:[1,0,1]
	v_pk_fma_f32 v[60:61], v[60:61], v[154:155], v[116:117] op_sel_hi:[1,0,1]
	v_mov_b32_e32 v116, v120
	v_mov_b32_e32 v117, v121
.LBB0_2766:
	s_or_b64 exec, exec, s[24:25]
	v_add_f32_e32 v84, v149, v150
	v_fma_f32 v84, -v129, v148, v84
	v_cndmask_b32_e32 v145, v135, v84, vcc
	v_add_f32_e32 v84, v97, v147
	v_fma_f32 v84, -v129, v95, v84
	v_cndmask_b32_e64 v97, v135, v84, s[10:11]
	v_add_f32_e32 v84, v93, v146
	v_fma_f32 v84, -v129, v90, v84
	v_cndmask_b32_e64 v85, v135, v84, s[12:13]
	v_add_f32_e32 v84, v89, v144
	v_fma_f32 v84, -v129, v87, v84
	v_max3_f32 v147, v145, s35, v97
	v_cndmask_b32_e64 v84, v135, v84, s[14:15]
	v_max3_f32 v89, v147, v85, v84
	ds_bpermute_b32 v93, v142, v89
	s_waitcnt lgkmcnt(0)
	v_max_f32_e32 v93, v93, v93
	v_max_f32_e32 v89, v89, v93
	ds_bpermute_b32 v93, v143, v89
	s_waitcnt lgkmcnt(0)
	v_max_f32_e32 v93, v93, v93
	v_max_f32_e32 v89, v89, v93
	v_cmp_neq_f32_e64 s[16:17], s35, v89
	s_and_saveexec_b64 s[24:25], s[16:17]
	s_cbranch_execz .LBB0_2768
	v_max_f32_e32 v89, v89, v89
	v_max_f32_e32 v93, v115, v115
	v_max_f32_e32 v123, v93, v89
	v_sub_f32_e32 v93, v145, v123
	v_mul_f32_e32 v93, 0x3fb8aa3b, v93
	v_exp_f32_e32 v122, v93
	v_sub_f32_e32 v97, v97, v123
	v_mul_f32_e32 v97, 0x3fb8aa3b, v97
	v_sub_f32_e32 v85, v85, v123
	v_add_f32_e32 v93, 0, v122
	v_pk_fma_f32 v[144:145], v[76:77], v[122:123], 0 op_sel_hi:[1,0,0]
	v_pk_fma_f32 v[146:147], v[74:75], v[122:123], 0 op_sel_hi:[1,0,0]
	v_exp_f32_e32 v122, v97
	v_mul_f32_e32 v85, 0x3fb8aa3b, v85
	v_sub_f32_e32 v84, v84, v123
	v_mul_f32_e32 v84, 0x3fb8aa3b, v84
	v_add_f32_e32 v93, v122, v93
	v_pk_fma_f32 v[144:145], v[68:69], v[122:123], v[144:145] op_sel_hi:[1,0,1]
	v_pk_fma_f32 v[146:147], v[66:67], v[122:123], v[146:147] op_sel_hi:[1,0,1]
	v_exp_f32_e32 v122, v85
	v_exp_f32_e32 v84, v84
	v_sub_f32_e32 v89, v115, v123
	v_mul_f32_e32 v89, 0x3fb8aa3b, v89
	v_add_f32_e32 v85, v122, v93
	v_pk_fma_f32 v[146:147], v[70:71], v[122:123], v[146:147] op_sel_hi:[1,0,1]
	v_pk_fma_f32 v[144:145], v[72:73], v[122:123], v[144:145] op_sel_hi:[1,0,1]
	v_add_f32_e32 v93, v84, v85
	v_pk_fma_f32 v[144:145], v[80:81], v[84:85], v[144:145] op_sel_hi:[1,0,1]
	v_pk_fma_f32 v[84:85], v[78:79], v[84:85], v[146:147] op_sel_hi:[1,0,1]
	v_exp_f32_e32 v146, v89
	ds_bpermute_b32 v89, v142, v93
	ds_bpermute_b32 v115, v142, v85
	ds_bpermute_b32 v150, v142, v144
	ds_bpermute_b32 v151, v142, v145
	s_waitcnt lgkmcnt(0)
	v_add_f32_e32 v89, v93, v89
	ds_bpermute_b32 v93, v143, v89
	s_waitcnt lgkmcnt(0)
	v_pk_add_f32 v[144:145], v[144:145], v[150:151]
	ds_bpermute_b32 v150, v143, v144
	ds_bpermute_b32 v151, v143, v145
	s_waitcnt lgkmcnt(0)
	v_add_f32_e32 v122, v89, v93
	v_fmac_f32_e32 v122, v114, v146
	ds_bpermute_b32 v114, v142, v84
	s_waitcnt lgkmcnt(0)
	v_pk_add_f32 v[84:85], v[84:85], v[114:115]
	ds_bpermute_b32 v114, v143, v84
	ds_bpermute_b32 v115, v143, v85
	s_waitcnt lgkmcnt(0)
	v_pk_add_f32 v[84:85], v[84:85], v[114:115]
	v_pk_add_f32 v[114:115], v[144:145], v[150:151]
	v_pk_fma_f32 v[50:51], v[50:51], v[146:147], v[84:85] op_sel_hi:[1,0,1]
	v_pk_fma_f32 v[52:53], v[52:53], v[146:147], v[114:115] op_sel_hi:[1,0,1]
	v_mov_b32_e32 v114, v122
	v_mov_b32_e32 v115, v123
.LBB0_2768:
	s_or_b64 exec, exec, s[24:25]
	v_add_f32_e32 v84, v94, v96
	v_fma_f32 v84, -v130, v148, v84
	v_cndmask_b32_e32 v89, v135, v84, vcc
	v_add_f32_e32 v84, v91, v92
	v_fma_f32 v84, -v130, v95, v84
	v_cndmask_b32_e64 v85, v135, v84, s[10:11]
	v_add_f32_e32 v84, v86, v88
	v_add_f32_e32 v82, v82, v83
	v_fma_f32 v84, -v130, v90, v84
	v_fma_f32 v82, -v130, v87, v82
	v_max3_f32 v91, v89, s35, v85
	v_cndmask_b32_e64 v84, v135, v84, s[12:13]
	v_cndmask_b32_e64 v82, v135, v82, s[14:15]
	v_max3_f32 v83, v91, v84, v82
	ds_bpermute_b32 v86, v142, v83
	s_waitcnt lgkmcnt(0)
	v_max_f32_e32 v86, v86, v86
	v_max_f32_e32 v83, v83, v86
	ds_bpermute_b32 v86, v143, v83
	s_waitcnt lgkmcnt(0)
	v_max_f32_e32 v86, v86, v86
	v_max_f32_e32 v83, v83, v86
	v_cmp_neq_f32_e32 vcc, s35, v83
	s_and_saveexec_b64 s[10:11], vcc
	s_cbranch_execz .LBB0_2770
	v_max_f32_e32 v83, v83, v83
	v_max_f32_e32 v86, v111, v111
	v_max_f32_e32 v125, v86, v83
	v_sub_f32_e32 v86, v89, v125
	v_mul_f32_e32 v86, 0x3fb8aa3b, v86
	v_exp_f32_e32 v86, v86
	v_sub_f32_e32 v85, v85, v125
	v_mul_f32_e32 v85, 0x3fb8aa3b, v85
	v_sub_f32_e32 v83, v111, v125
	v_add_f32_e32 v87, 0, v86
	v_pk_fma_f32 v[76:77], v[76:77], v[86:87], 0 op_sel_hi:[1,0,0]
	v_pk_fma_f32 v[74:75], v[74:75], v[86:87], 0 op_sel_hi:[1,0,0]
	v_exp_f32_e32 v86, v85
	v_mul_f32_e32 v83, 0x3fb8aa3b, v83
	v_mov_b32_e32 v111, v125
	v_pk_fma_f32 v[66:67], v[66:67], v[86:87], v[74:75] op_sel_hi:[1,0,1]
	v_sub_f32_e32 v74, v84, v125
	v_mul_f32_e32 v74, 0x3fb8aa3b, v74
	v_exp_f32_e32 v74, v74
	v_add_f32_e32 v85, v86, v87
	v_pk_fma_f32 v[68:69], v[68:69], v[86:87], v[76:77] op_sel_hi:[1,0,1]
	v_add_f32_e32 v75, v74, v85
	v_pk_fma_f32 v[66:67], v[70:71], v[74:75], v[66:67] op_sel_hi:[1,0,1]
	v_sub_f32_e32 v70, v82, v125
	v_mul_f32_e32 v70, 0x3fb8aa3b, v70
	v_exp_f32_e32 v70, v70
	v_pk_fma_f32 v[68:69], v[72:73], v[74:75], v[68:69] op_sel_hi:[1,0,1]
	v_add_f32_e32 v71, v70, v75
	ds_bpermute_b32 v72, v142, v71
	v_pk_fma_f32 v[68:69], v[80:81], v[70:71], v[68:69] op_sel_hi:[1,0,1]
	v_pk_fma_f32 v[66:67], v[78:79], v[70:71], v[66:67] op_sel_hi:[1,0,1]
	ds_bpermute_b32 v73, v142, v67
	ds_bpermute_b32 v74, v142, v68
	s_waitcnt lgkmcnt(0)
	v_add_f32_e32 v71, v71, v72
	ds_bpermute_b32 v72, v143, v71
	ds_bpermute_b32 v75, v142, v69
	v_exp_f32_e32 v70, v83
	s_waitcnt lgkmcnt(0)
	v_add_f32_e32 v124, v71, v72
	ds_bpermute_b32 v72, v142, v66
	s_waitcnt lgkmcnt(0)
	v_pk_add_f32 v[68:69], v[68:69], v[74:75]
	ds_bpermute_b32 v74, v143, v68
	ds_bpermute_b32 v75, v143, v69
	v_fmac_f32_e32 v124, v110, v70
	s_waitcnt lgkmcnt(0)
	v_pk_add_f32 v[66:67], v[66:67], v[72:73]
	ds_bpermute_b32 v72, v143, v66
	ds_bpermute_b32 v73, v143, v67
	s_waitcnt lgkmcnt(0)
	v_pk_add_f32 v[68:69], v[68:69], v[74:75]
	v_mov_b32_e32 v110, v124
	v_pk_fma_f32 v[44:45], v[44:45], v[70:71], v[68:69] op_sel_hi:[1,0,1]
	s_waitcnt lgkmcnt(0)
	v_pk_add_f32 v[66:67], v[66:67], v[72:73]
	s_nop 0
	v_pk_fma_f32 v[42:43], v[42:43], v[70:71], v[66:67] op_sel_hi:[1,0,1]

.LBB0_2794:
	v_max_u32_e32 v54, v1, v34
	v_max3_u32 v54, v54, v35, v36
	v_max3_u32 v54, v54, v37, v38
	v_max3_u32 v54, v54, v39, v40
	v_max3_u32 v54, v54, v41, v42
	v_max3_u32 v54, v54, v43, v44
	v_max3_u32 v54, v54, v45, v46
	v_max3_u32 v54, v54, v47, v48
	s_add_i32 s14, s14, -1
	s_cmp_eq_u32 s14, 0
	s_waitcnt lgkmcnt(0)
	s_nop 1
	v_max_u32_dpp v54, v54, v54 quad_perm:[1,0,3,2] row_mask:0xf bank_mask:0xf
	s_nop 1
	v_max_u32_dpp v54, v54, v54 quad_perm:[2,3,0,1] row_mask:0xf bank_mask:0xf
	s_nop 1
	v_max_u32_dpp v54, v54, v54 row_half_mirror row_mask:0xf bank_mask:0xf
	v_cmp_ne_u32_e64 s[6:7], v1, v54
	v_not_b32_e32 v55, v54
	v_bitop3_b32 v56, v54, s3, v54 bitop3:0xc
	v_cndmask_b32_e64 v1, 0, v1, s[6:7]
	v_cmp_ne_u32_e64 s[6:7], v34, v54
	v_lshlrev_b32_e64 v57, v55, 1
	v_bfe_u32 v55, v55, 5, 2
	v_cndmask_b32_e64 v34, 0, v34, s[6:7]
	v_cmp_ne_u32_e64 s[6:7], v35, v54
	v_cmp_eq_u32_e64 s[8:9], 2, v55
	s_nop 0
	v_cndmask_b32_e64 v35, 0, v35, s[6:7]
	v_cmp_ne_u32_e64 s[6:7], v36, v54
	s_nop 1
	v_cndmask_b32_e64 v36, 0, v36, s[6:7]
	v_cmp_ne_u32_e64 s[6:7], v37, v54
	s_nop 1
	v_cndmask_b32_e64 v37, 0, v37, s[6:7]
	v_cmp_ne_u32_e64 s[6:7], v38, v54
	s_nop 1
	v_cndmask_b32_e64 v38, 0, v38, s[6:7]
	v_cmp_ne_u32_e64 s[6:7], v39, v54
	s_nop 1
	v_cndmask_b32_e64 v39, 0, v39, s[6:7]
	v_cmp_ne_u32_e64 s[6:7], v40, v54
	s_nop 1
	v_cndmask_b32_e64 v40, 0, v40, s[6:7]
	v_cmp_ne_u32_e64 s[6:7], v41, v54
	s_nop 1
	v_cndmask_b32_e64 v41, 0, v41, s[6:7]
	v_cmp_ne_u32_e64 s[6:7], v42, v54
	s_nop 1
	v_cndmask_b32_e64 v42, 0, v42, s[6:7]
	v_cmp_ne_u32_e64 s[6:7], v43, v54
	s_nop 1
	v_cndmask_b32_e64 v43, 0, v43, s[6:7]
	v_cmp_ne_u32_e64 s[6:7], v44, v54
	s_nop 1
	v_cndmask_b32_e64 v44, 0, v44, s[6:7]
	v_cmp_ne_u32_e64 s[6:7], v45, v54
	s_nop 1
	v_cndmask_b32_e64 v45, 0, v45, s[6:7]
	v_cmp_ne_u32_e64 s[6:7], v46, v54
	s_nop 1
	v_cndmask_b32_e64 v46, 0, v46, s[6:7]
	v_cmp_ne_u32_e64 s[6:7], v47, v54
	s_nop 1
	v_cndmask_b32_e64 v47, 0, v47, s[6:7]
	v_cmp_ne_u32_e64 s[6:7], v48, v54
	s_nop 1
	v_cndmask_b32_e64 v48, 0, v48, s[6:7]
	v_cmp_ne_u32_e64 s[6:7], 0, v54
	s_nop 1
	v_cndmask_b32_e64 v54, 0, v57, s[6:7]
	v_cmp_gt_u32_e64 s[6:7], 32, v56
	s_nop 1
	v_cndmask_b32_e64 v56, 0, v54, s[6:7]
	v_cmp_eq_u32_e64 s[6:7], 1, v55
	v_or_b32_e32 v49, v56, v49
	v_cndmask_b32_e64 v56, 0, v54, s[8:9]
	v_cndmask_b32_e64 v57, 0, v54, s[6:7]
	v_cmp_eq_u32_e64 s[6:7], 3, v55
	v_or_b32_e32 v53, v56, v53
	v_or_b32_e32 v52, v57, v52
	v_cndmask_b32_e64 v54, 0, v54, s[6:7]
	v_or_b32_e32 v51, v54, v51
	s_cbranch_scc0 .LBB0_2794
	s_add_i32 s12, s5, 0x19000
	s_and_saveexec_b64 s[6:7], vcc
	s_cbranch_execz .LBB0_2797
	s_lshl_b32 s8, s28, 7
	s_add_i32 s8, s12, s8
	v_lshl_add_u32 v1, v93, 4, s8
	ds_write2_b32 v1, v52, v53 offset0:1 offset1:2
	ds_write2_b32 v1, v49, v51 offset1:3

.LBB0_5341:
	s_lshr_b32 s10, s48, 2
	s_cmp_lt_u32 s48, 4
	s_cselect_b64 vcc, -1, 0
	s_cmp_eq_u32 s10, 2
	s_cselect_b32 s12, s31, s29
	s_cselect_b32 s13, s42, s30
	s_cmp_eq_u32 s10, 1
	s_cselect_b64 s[10:11], -1, 0
	v_cndmask_b32_e64 v66, v106, v108, s[10:11]
	v_cndmask_b32_e64 v67, v107, v109, s[10:11]
	s_and_b64 s[10:11], s[10:11], exec
	s_cselect_b32 s14, s27, s28
	s_and_b64 s[10:11], vcc, exec
	s_cselect_b32 s14, s26, s14
	s_sub_i32 s10, s43, 32
	s_and_b32 s15, s10, 32
	s_or_b32 s10, s15, s14
	v_add_u32_e32 v80, s10, v100
	v_add_u32_e32 v144, 16, v80
	v_cndmask_b32_e32 v78, v66, v104, vcc
	v_subrev_u32_e32 v66, s14, v144
	v_cndmask_b32_e32 v79, v67, v105, vcc
	v_ashrrev_i32_e32 v67, 31, v66
	v_lshlrev_b64 v[66:67], 10, v[66:67]
	v_lshl_add_u64 v[66:67], v[78:79], 0, v[66:67]
	v_mov_b32_e32 v82, s13
	v_cmp_gt_i32_e64 s[10:11], s44, v144
	v_mov_b32_e32 v83, s12
	v_add_u32_e32 v147, 20, v80
	v_cndmask_b32_e64 v67, v82, v67, s[10:11]
	v_cndmask_b32_e64 v66, v83, v66, s[10:11]
	v_lshl_add_u64 v[66:67], v[66:67], 0, v[98:99]
	v_add_u32_e32 v146, 24, v80
	v_add_u32_e32 v145, 28, v80
	global_load_dwordx4 v[94:97], v[66:67], off
	global_load_dwordx4 v[74:77], v[66:67], off offset:512
	v_subrev_u32_e32 v66, s14, v147
	v_subrev_u32_e32 v70, s14, v146
	v_subrev_u32_e32 v80, s14, v145
	v_ashrrev_i32_e32 v67, 31, v66
	v_ashrrev_i32_e32 v71, 31, v70
	v_ashrrev_i32_e32 v81, 31, v80
	v_lshlrev_b64 v[66:67], 10, v[66:67]
	v_lshlrev_b64 v[70:71], 10, v[70:71]
	v_lshlrev_b64 v[80:81], 10, v[80:81]
	v_lshl_add_u64 v[66:67], v[78:79], 0, v[66:67]
	v_lshl_add_u64 v[70:71], v[78:79], 0, v[70:71]
	v_lshl_add_u64 v[78:79], v[78:79], 0, v[80:81]
	s_waitcnt vmcnt(0) lgkmcnt(0)
	v_mul_f32_e32 v80, v11, v3
	v_fmac_f32_e32 v80, v10, v2
	v_fmac_f32_e32 v80, v12, v4
	v_fmac_f32_e32 v80, v13, v5
	v_cmp_gt_i32_e64 s[10:11], s44, v147
	v_mul_f32_e32 v148, v11, v27
	v_fmac_f32_e32 v148, v10, v26
	v_cndmask_b32_e64 v67, v82, v67, s[10:11]
	s_waitcnt lgkmcnt(0)
	v_add_f32_dpp v80, v80, v80 quad_perm:[1,0,3,2] row_mask:0xf bank_mask:0xf
	v_cndmask_b32_e64 v66, v83, v66, s[10:11]
	v_cmp_gt_i32_e64 s[10:11], s44, v146
	v_mul_f32_e32 v125, v23, v3
	v_cndmask_b32_e64 v71, v82, v71, s[10:11]
	v_cndmask_b32_e64 v70, v83, v70, s[10:11]
	v_cmp_gt_i32_e64 s[10:11], s44, v145
	s_waitcnt lgkmcnt(0)
	v_add_f32_dpp v80, v80, v80 quad_perm:[2,3,0,1] row_mask:0xf bank_mask:0xf
	v_cndmask_b32_e64 v79, v82, v79, s[10:11]
	v_mul_f32_e32 v82, v15, v3
	v_fmac_f32_e32 v82, v14, v2
	v_fmac_f32_e32 v82, v16, v4
	v_fmac_f32_e32 v82, v17, v5
	v_cndmask_b32_e64 v78, v83, v78, s[10:11]
	s_and_b32 s10, s48, 12
	s_waitcnt lgkmcnt(0)
	v_add_f32_dpp v118, v80, v80 row_half_mirror row_mask:0xf bank_mask:0xf
	s_cmp_eq_u32 s10, 4
	s_waitcnt lgkmcnt(0)
	v_add_f32_dpp v120, v82, v82 quad_perm:[1,0,3,2] row_mask:0xf bank_mask:0xf
	s_cselect_b32 s12, s27, s28
	s_and_b64 s[10:11], vcc, exec
	s_cselect_b32 s10, s26, s12
	s_or_b32 s10, s10, s15
	v_add_u32_e32 v156, s10, v100
	v_sub_u32_e32 v84, 0x800, v156
	s_waitcnt lgkmcnt(0)
	v_add_f32_dpp v118, v118, v118 row_mirror row_mask:0xf bank_mask:0xf
	s_waitcnt lgkmcnt(0)
	v_add_f32_dpp v119, v120, v120 quad_perm:[2,3,0,1] row_mask:0xf bank_mask:0xf
	v_cvt_f32_u32_e32 v124, v84
	v_cmp_gt_i32_e32 vcc, s2, v156
	v_fmac_f32_e32 v125, v22, v2
	v_fma_f32 v118, -v127, v124, v118
	v_cndmask_b32_e32 v169, v135, v118, vcc
	s_waitcnt lgkmcnt(0)
	v_add_f32_dpp v120, v119, v119 row_half_mirror row_mask:0xf bank_mask:0xf
	v_pk_mul_f32 v[118:119], v[12:13], v[28:29]
	v_fmac_f32_e32 v125, v24, v4
	v_add_f32_e32 v118, v118, v148
	v_add_f32_e32 v118, v119, v118
	v_fmac_f32_e32 v125, v25, v5
	v_mul_f32_e32 v150, v15, v27
	v_fmac_f32_e32 v150, v14, v26
	s_waitcnt lgkmcnt(0)
	v_add_f32_dpp v118, v118, v118 quad_perm:[1,0,3,2] row_mask:0xf bank_mask:0xf
	v_fmac_f32_e32 v150, v16, v28
	s_waitcnt lgkmcnt(0)
	v_add_f32_dpp v125, v125, v125 quad_perm:[1,0,3,2] row_mask:0xf bank_mask:0xf
	v_fmac_f32_e32 v150, v17, v29
	ds_bpermute_b32 v148, v139, v125
	s_waitcnt lgkmcnt(0)
	v_add_f32_dpp v118, v118, v118 quad_perm:[2,3,0,1] row_mask:0xf bank_mask:0xf
	s_movk_i32 s10, 0x7fd
	s_waitcnt lgkmcnt(0)
	v_add_f32_e32 v148, v125, v148
	v_sub_u32_e32 v125, 0x7fc, v156
	s_waitcnt lgkmcnt(0)
	v_add_f32_dpp v118, v118, v118 row_half_mirror row_mask:0xf bank_mask:0xf
	v_cvt_f32_u32_e32 v125, v125
	v_cmp_gt_i32_e64 s[10:11], s10, v156
	v_mul_f32_e32 v154, v11, v35
	v_fmac_f32_e32 v154, v10, v34
	s_waitcnt lgkmcnt(0)
	v_add_f32_dpp v118, v118, v118 row_mirror row_mask:0xf bank_mask:0xf
	v_add_f32_dpp v119, v150, v150 quad_perm:[1,0,3,2] row_mask:0xf bank_mask:0xf
	v_mul_f32_e32 v151, v19, v27
	v_fma_f32 v118, -v127, v125, v118
	v_fmac_f32_e32 v151, v18, v26
	v_fmac_f32_e32 v151, v20, v28
	v_cndmask_b32_e64 v172, v135, v118, s[10:11]
	s_waitcnt lgkmcnt(0)
	v_add_f32_dpp v118, v119, v119 quad_perm:[2,3,0,1] row_mask:0xf bank_mask:0xf
	v_fmac_f32_e32 v151, v21, v29
	v_lshl_add_u64 v[66:67], v[66:67], 0, v[98:99]
	v_lshl_add_u64 v[70:71], v[70:71], 0, v[98:99]
	v_lshl_add_u64 v[78:79], v[78:79], 0, v[98:99]
	s_waitcnt lgkmcnt(0)
	v_add_f32_dpp v164, v118, v118 row_half_mirror row_mask:0xf bank_mask:0xf
	v_pk_mul_f32 v[118:119], v[12:13], v[36:37]
	s_waitcnt lgkmcnt(0)
	v_add_f32_dpp v150, v151, v151 quad_perm:[1,0,3,2] row_mask:0xf bank_mask:0xf
	v_mul_f32_e32 v152, v23, v27
	v_add_f32_e32 v118, v118, v154
	v_fmac_f32_e32 v152, v22, v26
	v_add_f32_e32 v118, v119, v118
	v_fmac_f32_e32 v152, v24, v28
	v_fmac_f32_e32 v152, v25, v29
	global_load_dwordx4 v[90:93], v[66:67], off
	s_nop 0
	global_load_dwordx4 v[66:69], v[66:67], off offset:512
	s_waitcnt lgkmcnt(0)
	v_add_f32_dpp v118, v118, v118 quad_perm:[1,0,3,2] row_mask:0xf bank_mask:0xf
	v_add_f32_dpp v152, v152, v152 quad_perm:[1,0,3,2] row_mask:0xf bank_mask:0xf
	global_load_dwordx4 v[86:89], v[70:71], off
	s_nop 0
	global_load_dwordx4 v[70:73], v[70:71], off offset:512
	s_nop 0
	global_load_dwordx4 v[82:85], v[78:79], off
	s_nop 0
	global_load_dwordx4 v[78:81], v[78:79], off offset:512
	v_mul_f32_e32 v154, v15, v35
	s_waitcnt lgkmcnt(0)
	v_add_f32_dpp v118, v118, v118 quad_perm:[2,3,0,1] row_mask:0xf bank_mask:0xf
	v_fmac_f32_e32 v154, v14, v34
	v_fmac_f32_e32 v154, v16, v36
	v_add_f32_dpp v150, v150, v150 quad_perm:[2,3,0,1] row_mask:0xf bank_mask:0xf
	v_add_f32_dpp v152, v152, v152 quad_perm:[2,3,0,1] row_mask:0xf bank_mask:0xf
	v_fmac_f32_e32 v154, v17, v37
	s_waitcnt lgkmcnt(0)
	v_add_f32_dpp v118, v118, v118 row_half_mirror row_mask:0xf bank_mask:0xf
	v_add_f32_dpp v158, v150, v150 row_half_mirror row_mask:0xf bank_mask:0xf
	v_add_f32_dpp v150, v152, v152 row_half_mirror row_mask:0xf bank_mask:0xf
	v_sub_u32_e32 v152, 0x7f8, v156
	v_add_f32_dpp v154, v154, v154 quad_perm:[1,0,3,2] row_mask:0xf bank_mask:0xf
	v_cvt_f32_u32_e32 v152, v152
	v_or_b32_e32 v153, 8, v156
	s_waitcnt lgkmcnt(0)
	v_add_f32_dpp v118, v118, v118 row_mirror row_mask:0xf bank_mask:0xf
	v_fma_f32 v118, -v127, v152, v118
	v_cmp_gt_i32_e64 s[12:13], s2, v153
	v_mul_f32_e32 v153, v19, v35
	v_fmac_f32_e32 v153, v18, v34
	v_cndmask_b32_e64 v173, v135, v118, s[12:13]
	v_add_f32_dpp v118, v154, v154 quad_perm:[2,3,0,1] row_mask:0xf bank_mask:0xf
	v_mul_f32_e32 v155, v23, v35
	v_fmac_f32_e32 v155, v22, v34
	v_fmac_f32_e32 v153, v20, v36
	v_fmac_f32_e32 v155, v24, v36
	v_fmac_f32_e32 v153, v21, v37
	v_fmac_f32_e32 v155, v25, v37
	ds_bpermute_b32 v160, v138, v155
	s_movk_i32 s14, 0x7f5
	v_cmp_gt_i32_e64 s[14:15], s14, v156
	s_waitcnt lgkmcnt(0)
	v_add_f32_dpp v153, v153, v153 quad_perm:[1,0,3,2] row_mask:0xf bank_mask:0xf
	v_add_f32_e32 v160, v155, v160
	v_pk_mul_f32 v[154:155], v[10:11], v[46:47]
	v_add_f32_dpp v167, v118, v118 row_half_mirror row_mask:0xf bank_mask:0xf
	v_pk_mul_f32 v[118:119], v[12:13], v[48:49]
	v_add_f32_e32 v154, v154, v155
	v_add_f32_e32 v118, v118, v154
	v_add_f32_e32 v118, v119, v118
	v_mul_f32_e32 v122, v19, v3
	s_waitcnt lgkmcnt(0)
	v_add_f32_dpp v153, v153, v153 quad_perm:[2,3,0,1] row_mask:0xf bank_mask:0xf
	v_add_f32_dpp v155, v160, v160 quad_perm:[2,3,0,1] row_mask:0xf bank_mask:0xf
	v_add_f32_dpp v118, v118, v118 quad_perm:[1,0,3,2] row_mask:0xf bank_mask:0xf
	v_fmac_f32_e32 v122, v18, v2
	s_waitcnt lgkmcnt(0)
	v_add_f32_dpp v160, v153, v153 row_half_mirror row_mask:0xf bank_mask:0xf
	v_add_f32_dpp v153, v155, v155 row_half_mirror row_mask:0xf bank_mask:0xf
	v_mul_f32_e32 v162, v15, v47
	v_add_f32_dpp v118, v118, v118 quad_perm:[2,3,0,1] row_mask:0xf bank_mask:0xf
	v_fmac_f32_e32 v162, v14, v46
	v_fmac_f32_e32 v162, v16, v48
	v_fmac_f32_e32 v162, v17, v49
	v_sub_u32_e32 v155, 0x7f4, v156
	s_waitcnt lgkmcnt(0)
	v_add_f32_dpp v118, v118, v118 row_half_mirror row_mask:0xf bank_mask:0xf
	v_cvt_f32_u32_e32 v155, v155
	v_add_f32_dpp v162, v162, v162 quad_perm:[1,0,3,2] row_mask:0xf bank_mask:0xf
	v_mul_f32_e32 v156, v19, v47
	s_waitcnt lgkmcnt(0)
	v_add_f32_dpp v118, v118, v118 row_mirror row_mask:0xf bank_mask:0xf
	v_fma_f32 v118, -v127, v155, v118
	v_cndmask_b32_e64 v174, v135, v118, s[14:15]
	v_add_f32_dpp v118, v162, v162 quad_perm:[2,3,0,1] row_mask:0xf bank_mask:0xf
	v_mul_f32_e32 v163, v23, v47
	v_fmac_f32_e32 v156, v18, v46
	v_fmac_f32_e32 v163, v22, v46
	v_fmac_f32_e32 v122, v20, v4
	v_fmac_f32_e32 v156, v20, v48
	v_fmac_f32_e32 v163, v24, v48
	v_fmac_f32_e32 v122, v21, v5
	v_fmac_f32_e32 v156, v21, v49
	v_fmac_f32_e32 v163, v25, v49
	v_max3_f32 v157, v169, s33, v172
	s_waitcnt lgkmcnt(0)
	v_add_f32_dpp v122, v122, v122 quad_perm:[1,0,3,2] row_mask:0xf bank_mask:0xf
	v_add_f32_dpp v170, v118, v118 row_half_mirror row_mask:0xf bank_mask:0xf
	v_add_f32_dpp v118, v156, v156 quad_perm:[1,0,3,2] row_mask:0xf bank_mask:0xf
	v_add_f32_dpp v156, v163, v163 quad_perm:[1,0,3,2] row_mask:0xf bank_mask:0xf
	v_max3_f32 v157, v157, v173, v174
	ds_bpermute_b32 v163, v142, v157
	s_waitcnt lgkmcnt(0)
	v_add_f32_dpp v122, v122, v122 quad_perm:[2,3,0,1] row_mask:0xf bank_mask:0xf
	v_add_f32_dpp v118, v118, v118 quad_perm:[2,3,0,1] row_mask:0xf bank_mask:0xf
	v_add_f32_dpp v156, v156, v156 quad_perm:[2,3,0,1] row_mask:0xf bank_mask:0xf
	v_max_f32_e32 v162, v163, v163
	v_max_f32_e32 v176, v157, v162
	ds_bpermute_b32 v177, v143, v176
	s_waitcnt lgkmcnt(0)
	v_add_f32_dpp v122, v122, v122 row_half_mirror row_mask:0xf bank_mask:0xf
	v_add_f32_dpp v148, v148, v148 row_half_mirror row_mask:0xf bank_mask:0xf
	v_add_f32_dpp v162, v118, v118 row_half_mirror row_mask:0xf bank_mask:0xf
	v_add_f32_dpp v156, v156, v156 row_half_mirror row_mask:0xf bank_mask:0xf
	ds_bpermute_b32 v121, v141, v120
	ds_bpermute_b32 v123, v141, v122
	ds_bpermute_b32 v149, v141, v148
	ds_bpermute_b32 v165, v141, v164
	ds_bpermute_b32 v159, v141, v158
	ds_bpermute_b32 v151, v141, v150
	ds_bpermute_b32 v168, v141, v167
	ds_bpermute_b32 v161, v141, v160
	ds_bpermute_b32 v154, v141, v153
	ds_bpermute_b32 v171, v141, v170
	ds_bpermute_b32 v163, v141, v162
	ds_bpermute_b32 v157, v141, v156
	v_max_f32_e32 v118, v177, v177
	v_max_f32_e32 v175, v176, v118
	v_cmp_neq_f32_e64 s[16:17], s33, v175
	v_mov_b64_e32 v[118:119], v[112:113]
	s_and_saveexec_b64 s[22:23], s[16:17]
	s_cbranch_execz .LBB0_5343
	v_max_f32_e32 v118, v175, v175
	v_max_f32_e32 v119, v113, v113
	v_max_f32_e32 v119, v119, v118
	v_sub_f32_e32 v118, v169, v119
	v_mul_f32_e32 v118, 0x3fb8aa3b, v118
	v_exp_f32_e32 v118, v118
	v_sub_f32_e32 v113, v113, v119
	v_mul_f32_e32 v113, 0x3fb8aa3b, v113
	v_add_f32_e32 v169, 0, v118
	v_pk_fma_f32 v[176:177], v[8:9], v[118:119], 0 op_sel_hi:[1,0,0]
	v_pk_fma_f32 v[178:179], v[6:7], v[118:119], 0 op_sel_hi:[1,0,0]
	v_sub_f32_e32 v118, v172, v119
	v_mul_f32_e32 v118, 0x3fb8aa3b, v118
	v_exp_f32_e32 v118, v118
	s_nop 0
	v_add_f32_e32 v169, v118, v169
	v_pk_fma_f32 v[176:177], v[32:33], v[118:119], v[176:177] op_sel_hi:[1,0,1]
	v_pk_fma_f32 v[178:179], v[30:31], v[118:119], v[178:179] op_sel_hi:[1,0,1]
	v_sub_f32_e32 v118, v173, v119
	v_mul_f32_e32 v118, 0x3fb8aa3b, v118
	v_exp_f32_e32 v118, v118
	s_nop 0
	v_add_f32_e32 v169, v118, v169
	v_pk_fma_f32 v[172:173], v[38:39], v[118:119], v[178:179] op_sel_hi:[1,0,1]
	v_pk_fma_f32 v[176:177], v[40:41], v[118:119], v[176:177] op_sel_hi:[1,0,1]
	v_sub_f32_e32 v118, v174, v119
	v_mul_f32_e32 v118, 0x3fb8aa3b, v118
	v_exp_f32_e32 v118, v118
	s_nop 0
	v_add_f32_e32 v169, v118, v169
	v_pk_fma_f32 v[174:175], v[56:57], v[118:119], v[176:177] op_sel_hi:[1,0,1]
	v_exp_f32_e32 v176, v113
	ds_bpermute_b32 v113, v142, v169
	v_pk_fma_f32 v[172:173], v[54:55], v[118:119], v[172:173] op_sel_hi:[1,0,1]
	ds_bpermute_b32 v178, v142, v174
	ds_bpermute_b32 v179, v142, v175
	s_waitcnt lgkmcnt(0)
	v_add_f32_e32 v113, v169, v113
	ds_bpermute_b32 v118, v143, v113
	v_pk_add_f32 v[174:175], v[174:175], v[178:179]
	ds_bpermute_b32 v178, v143, v174
	ds_bpermute_b32 v179, v143, v175
	s_waitcnt lgkmcnt(0)
	v_add_f32_e32 v118, v113, v118
	v_fmac_f32_e32 v118, v112, v176
	ds_bpermute_b32 v112, v142, v172
	ds_bpermute_b32 v113, v142, v173
	s_waitcnt lgkmcnt(0)
	v_pk_add_f32 v[112:113], v[172:173], v[112:113]
	ds_bpermute_b32 v172, v143, v112
	ds_bpermute_b32 v173, v143, v113
	s_waitcnt lgkmcnt(0)
	v_pk_add_f32 v[112:113], v[112:113], v[172:173]
	v_pk_add_f32 v[172:173], v[174:175], v[178:179]
	v_pk_fma_f32 v[62:63], v[62:63], v[176:177], v[112:113] op_sel_hi:[1,0,1]
	v_pk_fma_f32 v[64:65], v[64:65], v[176:177], v[172:173] op_sel_hi:[1,0,1]
	v_mov_b32_e32 v112, v118
	v_mov_b32_e32 v113, v119

.LBB0_5351:
	v_mul_f32_e32 v149, v11, v95
	v_fmac_f32_e32 v149, v10, v94
	v_fmac_f32_e32 v149, v12, v96
	v_fmac_f32_e32 v149, v13, v97
	v_sub_u32_e32 v148, 0x800, v144
	v_cvt_f32_u32_e32 v148, v148
	v_cmp_gt_i32_e32 vcc, s2, v144
	s_waitcnt vmcnt(0)
	v_pk_mul_f32 v[154:155], v[12:13], v[92:93]
	s_waitcnt lgkmcnt(0)
	v_add_f32_dpp v149, v149, v149 quad_perm:[1,0,3,2] row_mask:0xf bank_mask:0xf
	v_cmp_gt_i32_e64 s[10:11], s2, v147
	v_pk_mul_f32 v[158:159], v[12:13], v[88:89]
	v_cmp_gt_i32_e64 s[12:13], s2, v146
	v_pk_mul_f32 v[160:161], v[10:11], v[82:83]
	s_waitcnt lgkmcnt(0)
	v_add_f32_dpp v149, v149, v149 quad_perm:[2,3,0,1] row_mask:0xf bank_mask:0xf
	v_cmp_gt_i32_e64 s[14:15], s2, v145
	s_waitcnt lgkmcnt(0)
	v_add_f32_dpp v149, v149, v149 row_half_mirror row_mask:0xf bank_mask:0xf
	s_waitcnt lgkmcnt(0)
	s_nop 0
	v_add_f32_dpp v149, v149, v149 row_mirror row_mask:0xf bank_mask:0xf
	v_fma_f32 v149, -v127, v148, v149
	v_cndmask_b32_e32 v153, v135, v149, vcc
	v_mul_f32_e32 v149, v15, v95
	v_fmac_f32_e32 v149, v14, v94
	v_fmac_f32_e32 v149, v16, v96
	v_fmac_f32_e32 v149, v17, v97
	s_waitcnt lgkmcnt(0)
	s_nop 0
	v_add_f32_dpp v149, v149, v149 quad_perm:[1,0,3,2] row_mask:0xf bank_mask:0xf
	s_waitcnt lgkmcnt(0)
	s_nop 0
	v_add_f32_dpp v149, v149, v149 quad_perm:[2,3,0,1] row_mask:0xf bank_mask:0xf
	s_waitcnt lgkmcnt(0)
	s_nop 0
	v_add_f32_dpp v151, v149, v149 row_half_mirror row_mask:0xf bank_mask:0xf
	v_mul_f32_e32 v149, v19, v95
	v_mul_f32_e32 v95, v23, v95
	v_fmac_f32_e32 v149, v18, v94
	v_fmac_f32_e32 v95, v22, v94
	v_fmac_f32_e32 v149, v20, v96
	v_fmac_f32_e32 v95, v24, v96
	v_fmac_f32_e32 v149, v21, v97
	v_fmac_f32_e32 v95, v25, v97
	v_mul_f32_e32 v97, v11, v91
	v_fmac_f32_e32 v97, v10, v90
	v_add_f32_e32 v97, v154, v97
	v_add_f32_e32 v97, v155, v97
	ds_bpermute_b32 v94, v138, v95
	ds_bpermute_b32 v152, v141, v151
	s_waitcnt lgkmcnt(0)
	v_add_f32_dpp v97, v97, v97 quad_perm:[1,0,3,2] row_mask:0xf bank_mask:0xf
	s_waitcnt lgkmcnt(0)
	v_add_f32_e32 v94, v95, v94
	s_waitcnt lgkmcnt(0)
	v_add_f32_dpp v149, v149, v149 quad_perm:[1,0,3,2] row_mask:0xf bank_mask:0xf
	s_waitcnt lgkmcnt(0)
	v_add_f32_dpp v97, v97, v97 quad_perm:[2,3,0,1] row_mask:0xf bank_mask:0xf
	s_waitcnt lgkmcnt(0)
	v_add_f32_dpp v94, v94, v94 quad_perm:[2,3,0,1] row_mask:0xf bank_mask:0xf
	s_waitcnt lgkmcnt(0)
	v_add_f32_dpp v149, v149, v149 quad_perm:[2,3,0,1] row_mask:0xf bank_mask:0xf
	s_waitcnt lgkmcnt(0)
	v_add_f32_dpp v97, v97, v97 row_half_mirror row_mask:0xf bank_mask:0xf
	s_waitcnt lgkmcnt(0)
	v_add_f32_dpp v94, v94, v94 row_half_mirror row_mask:0xf bank_mask:0xf
	v_sub_u32_e32 v95, 0x7fc, v144
	v_cvt_f32_u32_e32 v95, v95
	s_waitcnt lgkmcnt(0)
	v_add_f32_dpp v149, v149, v149 row_half_mirror row_mask:0xf bank_mask:0xf
	s_waitcnt lgkmcnt(0)
	v_add_f32_dpp v97, v97, v97 row_mirror row_mask:0xf bank_mask:0xf
	ds_bpermute_b32 v150, v141, v149
	v_fma_f32 v97, -v127, v95, v97
	v_cndmask_b32_e64 v156, v135, v97, s[10:11]
	v_mul_f32_e32 v97, v15, v91
	v_fmac_f32_e32 v97, v14, v90
	v_fmac_f32_e32 v97, v16, v92
	v_fmac_f32_e32 v97, v17, v93
	v_max3_f32 v162, v153, s33, v156
	ds_bpermute_b32 v96, v141, v94
	s_waitcnt lgkmcnt(0)
	v_add_f32_dpp v97, v97, v97 quad_perm:[1,0,3,2] row_mask:0xf bank_mask:0xf
	s_waitcnt lgkmcnt(0)
	s_nop 0
	v_add_f32_dpp v97, v97, v97 quad_perm:[2,3,0,1] row_mask:0xf bank_mask:0xf
	s_waitcnt lgkmcnt(0)
	s_nop 0
	v_add_f32_dpp v154, v97, v97 row_half_mirror row_mask:0xf bank_mask:0xf
	v_mul_f32_e32 v97, v19, v91
	v_mul_f32_e32 v91, v23, v91
	v_fmac_f32_e32 v97, v18, v90
	v_fmac_f32_e32 v91, v22, v90
	v_fmac_f32_e32 v97, v20, v92
	v_fmac_f32_e32 v91, v24, v92
	v_fmac_f32_e32 v97, v21, v93
	v_fmac_f32_e32 v91, v25, v93
	v_mul_f32_e32 v93, v11, v87
	v_fmac_f32_e32 v93, v10, v86
	v_add_f32_e32 v93, v158, v93
	v_add_f32_e32 v93, v159, v93
	ds_bpermute_b32 v90, v138, v91
	ds_bpermute_b32 v155, v141, v154
	s_waitcnt lgkmcnt(0)
	v_add_f32_dpp v93, v93, v93 quad_perm:[1,0,3,2] row_mask:0xf bank_mask:0xf
	s_waitcnt lgkmcnt(0)
	v_add_f32_e32 v90, v91, v90
	s_waitcnt lgkmcnt(0)
	v_add_f32_dpp v97, v97, v97 quad_perm:[1,0,3,2] row_mask:0xf bank_mask:0xf
	s_waitcnt lgkmcnt(0)
	v_add_f32_dpp v93, v93, v93 quad_perm:[2,3,0,1] row_mask:0xf bank_mask:0xf
	s_waitcnt lgkmcnt(0)
	v_add_f32_dpp v90, v90, v90 quad_perm:[2,3,0,1] row_mask:0xf bank_mask:0xf
	ds_bpermute_b32 v91, v140, v90
	s_waitcnt lgkmcnt(0)
	v_add_f32_dpp v97, v97, v97 quad_perm:[2,3,0,1] row_mask:0xf bank_mask:0xf
	s_waitcnt lgkmcnt(0)
	v_add_f32_dpp v93, v93, v93 row_half_mirror row_mask:0xf bank_mask:0xf
	s_waitcnt lgkmcnt(0)
	v_add_f32_e32 v91, v90, v91
	v_sub_u32_e32 v90, 0x7f8, v144
	v_cvt_f32_u32_e32 v90, v90
	s_waitcnt lgkmcnt(0)
	v_add_f32_dpp v97, v97, v97 row_half_mirror row_mask:0xf bank_mask:0xf
	s_waitcnt lgkmcnt(0)
	v_add_f32_dpp v93, v93, v93 row_mirror row_mask:0xf bank_mask:0xf
	ds_bpermute_b32 v147, v141, v97
	v_fma_f32 v93, -v127, v90, v93
	v_cndmask_b32_e64 v159, v135, v93, s[12:13]
	v_mul_f32_e32 v93, v15, v87
	v_fmac_f32_e32 v93, v14, v86
	v_fmac_f32_e32 v93, v16, v88
	v_fmac_f32_e32 v93, v17, v89
	ds_bpermute_b32 v92, v141, v91
	s_waitcnt lgkmcnt(0)
	v_add_f32_dpp v93, v93, v93 quad_perm:[1,0,3,2] row_mask:0xf bank_mask:0xf
	s_waitcnt lgkmcnt(0)
	s_nop 0
	v_add_f32_dpp v93, v93, v93 quad_perm:[2,3,0,1] row_mask:0xf bank_mask:0xf
	s_waitcnt lgkmcnt(0)
	s_nop 0
	v_add_f32_dpp v157, v93, v93 row_half_mirror row_mask:0xf bank_mask:0xf
	v_mul_f32_e32 v93, v19, v87
	v_mul_f32_e32 v87, v23, v87
	v_fmac_f32_e32 v87, v22, v86
	v_fmac_f32_e32 v87, v24, v88
	v_fmac_f32_e32 v87, v25, v89
	v_fmac_f32_e32 v93, v18, v86
	ds_bpermute_b32 v86, v138, v87
	v_fmac_f32_e32 v93, v20, v88
	v_fmac_f32_e32 v93, v21, v89
	v_add_f32_e32 v89, v160, v161
	s_waitcnt lgkmcnt(0)
	v_add_f32_e32 v86, v87, v86
	ds_bpermute_b32 v158, v141, v157
	s_waitcnt lgkmcnt(0)
	v_add_f32_dpp v93, v93, v93 quad_perm:[1,0,3,2] row_mask:0xf bank_mask:0xf
	s_waitcnt lgkmcnt(0)
	v_add_f32_dpp v86, v86, v86 quad_perm:[2,3,0,1] row_mask:0xf bank_mask:0xf
	s_waitcnt lgkmcnt(0)
	v_add_f32_dpp v93, v93, v93 quad_perm:[2,3,0,1] row_mask:0xf bank_mask:0xf
	s_waitcnt lgkmcnt(0)
	v_add_f32_dpp v86, v86, v86 row_half_mirror row_mask:0xf bank_mask:0xf
	v_sub_u32_e32 v87, 0x7f4, v144
	v_pk_mul_f32 v[144:145], v[12:13], v[84:85]
	v_cvt_f32_u32_e32 v87, v87
	v_add_f32_e32 v89, v144, v89
	v_add_f32_e32 v89, v145, v89
	s_waitcnt lgkmcnt(0)
	v_add_f32_dpp v93, v93, v93 row_half_mirror row_mask:0xf bank_mask:0xf
	ds_bpermute_b32 v146, v141, v93
	ds_bpermute_b32 v88, v141, v86
	s_waitcnt lgkmcnt(0)
	v_add_f32_dpp v89, v89, v89 quad_perm:[1,0,3,2] row_mask:0xf bank_mask:0xf
	s_waitcnt lgkmcnt(0)
	s_nop 0
	v_add_f32_dpp v89, v89, v89 quad_perm:[2,3,0,1] row_mask:0xf bank_mask:0xf
	s_waitcnt lgkmcnt(0)
	s_nop 0
	v_add_f32_dpp v89, v89, v89 row_half_mirror row_mask:0xf bank_mask:0xf
	s_waitcnt lgkmcnt(0)
	s_nop 0
	v_add_f32_dpp v89, v89, v89 row_mirror row_mask:0xf bank_mask:0xf
	v_fma_f32 v89, -v127, v87, v89
	v_cndmask_b32_e64 v161, v135, v89, s[14:15]
	v_mul_f32_e32 v89, v15, v83
	v_fmac_f32_e32 v89, v14, v82
	v_fmac_f32_e32 v89, v16, v84
	v_fmac_f32_e32 v89, v17, v85
	v_max3_f32 v162, v162, v159, v161
	s_waitcnt lgkmcnt(0)
	v_add_f32_dpp v89, v89, v89 quad_perm:[1,0,3,2] row_mask:0xf bank_mask:0xf
	s_waitcnt lgkmcnt(0)
	s_nop 0
	v_add_f32_dpp v89, v89, v89 quad_perm:[2,3,0,1] row_mask:0xf bank_mask:0xf
	s_waitcnt lgkmcnt(0)
	s_nop 0
	v_add_f32_dpp v145, v89, v89 row_half_mirror row_mask:0xf bank_mask:0xf
	v_mul_f32_e32 v89, v19, v83
	v_mul_f32_e32 v83, v23, v83
	v_fmac_f32_e32 v89, v18, v82
	v_fmac_f32_e32 v83, v22, v82
	v_fmac_f32_e32 v89, v20, v84
	v_fmac_f32_e32 v83, v24, v84
	v_fmac_f32_e32 v89, v21, v85
	v_fmac_f32_e32 v83, v25, v85
	ds_bpermute_b32 v82, v138, v83
	ds_bpermute_b32 v84, v142, v162
	ds_bpermute_b32 v160, v141, v145
	s_waitcnt lgkmcnt(0)
	v_add_f32_dpp v89, v89, v89 quad_perm:[1,0,3,2] row_mask:0xf bank_mask:0xf
	s_waitcnt lgkmcnt(0)
	v_add_f32_e32 v82, v83, v82
	s_waitcnt lgkmcnt(0)
	v_max_f32_e32 v84, v84, v84
	v_max_f32_e32 v84, v162, v84
	ds_bpermute_b32 v85, v143, v84
	s_waitcnt lgkmcnt(0)
	v_add_f32_dpp v89, v89, v89 quad_perm:[2,3,0,1] row_mask:0xf bank_mask:0xf
	s_waitcnt lgkmcnt(0)
	v_add_f32_dpp v82, v82, v82 quad_perm:[2,3,0,1] row_mask:0xf bank_mask:0xf
	s_waitcnt lgkmcnt(0)
	v_max_f32_e32 v85, v85, v85
	v_max_f32_e32 v84, v84, v85
	v_cmp_neq_f32_e64 s[16:17], s33, v84
	s_waitcnt lgkmcnt(0)
	v_add_f32_dpp v89, v89, v89 row_half_mirror row_mask:0xf bank_mask:0xf
	s_waitcnt lgkmcnt(0)
	v_add_f32_dpp v82, v82, v82 row_half_mirror row_mask:0xf bank_mask:0xf
	ds_bpermute_b32 v144, v141, v89
	ds_bpermute_b32 v83, v141, v82
	s_and_saveexec_b64 s[24:25], s[16:17]
	s_cbranch_execz .LBB0_5353
	v_max_f32_e32 v84, v84, v84
	v_max_f32_e32 v85, v113, v113
	v_max_f32_e32 v119, v85, v84
	v_sub_f32_e32 v84, v113, v119
	v_mul_f32_e32 v113, 0x3fb8aa3b, v84
	v_sub_f32_e32 v84, v153, v119
	v_mul_f32_e32 v84, 0x3fb8aa3b, v84
	v_sub_f32_e32 v118, v156, v119
	v_exp_f32_e32 v84, v84
	v_mul_f32_e32 v118, 0x3fb8aa3b, v118
	v_exp_f32_e32 v118, v118
	v_exp_f32_e32 v156, v113
	v_add_f32_e32 v153, 0, v84
	v_pk_fma_f32 v[162:163], v[76:77], v[84:85], 0 op_sel_hi:[1,0,0]
	v_pk_fma_f32 v[84:85], v[74:75], v[84:85], 0 op_sel_hi:[1,0,0]
	v_add_f32_e32 v153, v118, v153
	v_pk_fma_f32 v[162:163], v[68:69], v[118:119], v[162:163] op_sel_hi:[1,0,1]
	v_pk_fma_f32 v[84:85], v[66:67], v[118:119], v[84:85] op_sel_hi:[1,0,1]
	v_sub_f32_e32 v118, v159, v119
	v_mul_f32_e32 v118, 0x3fb8aa3b, v118
	v_exp_f32_e32 v118, v118
	s_nop 0
	v_add_f32_e32 v153, v118, v153
	v_pk_fma_f32 v[84:85], v[70:71], v[118:119], v[84:85] op_sel_hi:[1,0,1]
	v_pk_fma_f32 v[162:163], v[72:73], v[118:119], v[162:163] op_sel_hi:[1,0,1]
	v_sub_f32_e32 v118, v161, v119
	v_mul_f32_e32 v118, 0x3fb8aa3b, v118
	v_exp_f32_e32 v118, v118
	s_nop 0
	v_add_f32_e32 v153, v118, v153
	ds_bpermute_b32 v113, v142, v153
	v_pk_fma_f32 v[162:163], v[80:81], v[118:119], v[162:163] op_sel_hi:[1,0,1]
	v_pk_fma_f32 v[84:85], v[78:79], v[118:119], v[84:85] op_sel_hi:[1,0,1]
	ds_bpermute_b32 v164, v142, v162
	ds_bpermute_b32 v165, v142, v163
	s_waitcnt lgkmcnt(0)
	v_add_f32_e32 v113, v153, v113
	ds_bpermute_b32 v118, v143, v113
	s_waitcnt lgkmcnt(0)
	v_pk_add_f32 v[162:163], v[162:163], v[164:165]
	ds_bpermute_b32 v164, v143, v162
	s_waitcnt lgkmcnt(0)
	v_add_f32_e32 v118, v113, v118
	v_fmac_f32_e32 v118, v112, v156
	ds_bpermute_b32 v112, v142, v84
	ds_bpermute_b32 v113, v142, v85
	ds_bpermute_b32 v165, v143, v163
	s_waitcnt lgkmcnt(0)
	v_pk_add_f32 v[84:85], v[84:85], v[112:113]
	ds_bpermute_b32 v112, v143, v84
	ds_bpermute_b32 v113, v143, v85
	s_waitcnt lgkmcnt(0)
	v_pk_add_f32 v[84:85], v[84:85], v[112:113]
	v_pk_add_f32 v[112:113], v[162:163], v[164:165]
	v_pk_fma_f32 v[62:63], v[62:63], v[156:157], v[84:85] op_sel_hi:[1,0,1]
	v_pk_fma_f32 v[64:65], v[64:65], v[156:157], v[112:113] op_sel_hi:[1,0,1]
	v_mov_b32_e32 v112, v118
	v_mov_b32_e32 v113, v119
.LBB0_5353:
	s_or_b64 exec, exec, s[24:25]
	v_add_f32_e32 v84, v151, v152
	v_fma_f32 v84, -v128, v148, v84
	v_cndmask_b32_e32 v152, v135, v84, vcc
	v_add_f32_e32 v84, v154, v155
	v_fma_f32 v84, -v128, v95, v84
	v_cndmask_b32_e64 v151, v135, v84, s[10:11]
	v_add_f32_e32 v84, v157, v158
	v_fma_f32 v84, -v128, v90, v84
	v_cndmask_b32_e64 v85, v135, v84, s[12:13]
	v_add_f32_e32 v84, v145, v160
	v_fma_f32 v84, -v128, v87, v84
	v_max3_f32 v153, v152, s33, v151
	v_cndmask_b32_e64 v84, v135, v84, s[14:15]
	v_max3_f32 v145, v153, v85, v84
	ds_bpermute_b32 v153, v142, v145
	s_waitcnt lgkmcnt(0)
	v_max_f32_e32 v153, v153, v153
	v_max_f32_e32 v145, v145, v153
	ds_bpermute_b32 v153, v143, v145
	s_waitcnt lgkmcnt(0)
	v_max_f32_e32 v153, v153, v153
	v_max_f32_e32 v145, v145, v153
	v_cmp_neq_f32_e64 s[16:17], s33, v145
	s_and_saveexec_b64 s[24:25], s[16:17]
	s_cbranch_execz .LBB0_5355
	v_max_f32_e32 v120, v145, v145
	v_max_f32_e32 v121, v117, v117
	v_max_f32_e32 v121, v121, v120
	v_sub_f32_e32 v120, v152, v121
	v_mul_f32_e32 v120, 0x3fb8aa3b, v120
	v_exp_f32_e32 v120, v120
	v_sub_f32_e32 v85, v85, v121
	v_mul_f32_e32 v85, 0x3fb8aa3b, v85
	v_sub_f32_e32 v84, v84, v121
	v_add_f32_e32 v145, 0, v120
	v_pk_fma_f32 v[152:153], v[76:77], v[120:121], 0 op_sel_hi:[1,0,0]
	v_pk_fma_f32 v[154:155], v[74:75], v[120:121], 0 op_sel_hi:[1,0,0]
	v_sub_f32_e32 v120, v151, v121
	v_mul_f32_e32 v120, 0x3fb8aa3b, v120
	v_exp_f32_e32 v120, v120
	v_mul_f32_e32 v84, 0x3fb8aa3b, v84
	v_exp_f32_e32 v84, v84
	v_sub_f32_e32 v117, v117, v121
	v_add_f32_e32 v145, v120, v145
	v_pk_fma_f32 v[152:153], v[68:69], v[120:121], v[152:153] op_sel_hi:[1,0,1]
	v_pk_fma_f32 v[154:155], v[66:67], v[120:121], v[154:155] op_sel_hi:[1,0,1]
	v_exp_f32_e32 v120, v85
	v_mul_f32_e32 v117, 0x3fb8aa3b, v117
	v_add_f32_e32 v85, v120, v145
	v_pk_fma_f32 v[154:155], v[70:71], v[120:121], v[154:155] op_sel_hi:[1,0,1]
	v_pk_fma_f32 v[152:153], v[72:73], v[120:121], v[152:153] op_sel_hi:[1,0,1]
	v_add_f32_e32 v120, v84, v85
	v_pk_fma_f32 v[152:153], v[80:81], v[84:85], v[152:153] op_sel_hi:[1,0,1]
	v_pk_fma_f32 v[84:85], v[78:79], v[84:85], v[154:155] op_sel_hi:[1,0,1]
	v_exp_f32_e32 v154, v117
	ds_bpermute_b32 v117, v142, v120
	ds_bpermute_b32 v156, v142, v152
	ds_bpermute_b32 v157, v142, v153
	s_waitcnt lgkmcnt(0)
	v_add_f32_e32 v117, v120, v117
	ds_bpermute_b32 v120, v143, v117
	s_waitcnt lgkmcnt(0)
	v_pk_add_f32 v[152:153], v[152:153], v[156:157]
	ds_bpermute_b32 v156, v143, v152
	ds_bpermute_b32 v157, v143, v153
	s_waitcnt lgkmcnt(0)
	v_add_f32_e32 v120, v117, v120
	v_fmac_f32_e32 v120, v116, v154
	ds_bpermute_b32 v116, v142, v84
	ds_bpermute_b32 v117, v142, v85
	s_waitcnt lgkmcnt(0)
	v_pk_add_f32 v[84:85], v[84:85], v[116:117]
	ds_bpermute_b32 v116, v143, v84
	ds_bpermute_b32 v117, v143, v85
	s_waitcnt lgkmcnt(0)
	v_pk_add_f32 v[84:85], v[84:85], v[116:117]
	v_pk_add_f32 v[116:117], v[152:153], v[156:157]
	v_pk_fma_f32 v[58:59], v[58:59], v[154:155], v[84:85] op_sel_hi:[1,0,1]
	v_pk_fma_f32 v[60:61], v[60:61], v[154:155], v[116:117] op_sel_hi:[1,0,1]
	v_mov_b32_e32 v116, v120
	v_mov_b32_e32 v117, v121
.LBB0_5355:
	s_or_b64 exec, exec, s[24:25]
	v_add_f32_e32 v84, v149, v150
	v_fma_f32 v84, -v129, v148, v84
	v_cndmask_b32_e32 v145, v135, v84, vcc
	v_add_f32_e32 v84, v97, v147
	v_fma_f32 v84, -v129, v95, v84
	v_cndmask_b32_e64 v97, v135, v84, s[10:11]
	v_add_f32_e32 v84, v93, v146
	v_fma_f32 v84, -v129, v90, v84
	v_cndmask_b32_e64 v85, v135, v84, s[12:13]
	v_add_f32_e32 v84, v89, v144
	v_fma_f32 v84, -v129, v87, v84
	v_max3_f32 v147, v145, s33, v97
	v_cndmask_b32_e64 v84, v135, v84, s[14:15]
	v_max3_f32 v89, v147, v85, v84
	ds_bpermute_b32 v93, v142, v89
	s_waitcnt lgkmcnt(0)
	v_max_f32_e32 v93, v93, v93
	v_max_f32_e32 v89, v89, v93
	ds_bpermute_b32 v93, v143, v89
	s_waitcnt lgkmcnt(0)
	v_max_f32_e32 v93, v93, v93
	v_max_f32_e32 v89, v89, v93
	v_cmp_neq_f32_e64 s[16:17], s33, v89
	s_and_saveexec_b64 s[24:25], s[16:17]
	s_cbranch_execz .LBB0_5357
	v_max_f32_e32 v89, v89, v89
	v_max_f32_e32 v93, v115, v115
	v_max_f32_e32 v123, v93, v89
	v_sub_f32_e32 v93, v145, v123
	v_mul_f32_e32 v93, 0x3fb8aa3b, v93
	v_exp_f32_e32 v122, v93
	v_sub_f32_e32 v97, v97, v123
	v_mul_f32_e32 v97, 0x3fb8aa3b, v97
	v_sub_f32_e32 v85, v85, v123
	v_add_f32_e32 v93, 0, v122
	v_pk_fma_f32 v[144:145], v[76:77], v[122:123], 0 op_sel_hi:[1,0,0]
	v_pk_fma_f32 v[146:147], v[74:75], v[122:123], 0 op_sel_hi:[1,0,0]
	v_exp_f32_e32 v122, v97
	v_mul_f32_e32 v85, 0x3fb8aa3b, v85
	v_sub_f32_e32 v84, v84, v123
	v_mul_f32_e32 v84, 0x3fb8aa3b, v84
	v_add_f32_e32 v93, v122, v93
	v_pk_fma_f32 v[144:145], v[68:69], v[122:123], v[144:145] op_sel_hi:[1,0,1]
	v_pk_fma_f32 v[146:147], v[66:67], v[122:123], v[146:147] op_sel_hi:[1,0,1]
	v_exp_f32_e32 v122, v85
	v_exp_f32_e32 v84, v84
	v_sub_f32_e32 v89, v115, v123
	v_mul_f32_e32 v89, 0x3fb8aa3b, v89
	v_add_f32_e32 v85, v122, v93
	v_pk_fma_f32 v[146:147], v[70:71], v[122:123], v[146:147] op_sel_hi:[1,0,1]
	v_pk_fma_f32 v[144:145], v[72:73], v[122:123], v[144:145] op_sel_hi:[1,0,1]
	v_add_f32_e32 v93, v84, v85
	v_pk_fma_f32 v[144:145], v[80:81], v[84:85], v[144:145] op_sel_hi:[1,0,1]
	v_pk_fma_f32 v[84:85], v[78:79], v[84:85], v[146:147] op_sel_hi:[1,0,1]
	v_exp_f32_e32 v146, v89
	ds_bpermute_b32 v89, v142, v93
	ds_bpermute_b32 v115, v142, v85
	ds_bpermute_b32 v150, v142, v144
	ds_bpermute_b32 v151, v142, v145
	s_waitcnt lgkmcnt(0)
	v_add_f32_e32 v89, v93, v89
	ds_bpermute_b32 v93, v143, v89
	s_waitcnt lgkmcnt(0)
	v_pk_add_f32 v[144:145], v[144:145], v[150:151]
	ds_bpermute_b32 v150, v143, v144
	ds_bpermute_b32 v151, v143, v145
	s_waitcnt lgkmcnt(0)
	v_add_f32_e32 v122, v89, v93
	v_fmac_f32_e32 v122, v114, v146
	ds_bpermute_b32 v114, v142, v84
	s_waitcnt lgkmcnt(0)
	v_pk_add_f32 v[84:85], v[84:85], v[114:115]
	ds_bpermute_b32 v114, v143, v84
	ds_bpermute_b32 v115, v143, v85
	s_waitcnt lgkmcnt(0)
	v_pk_add_f32 v[84:85], v[84:85], v[114:115]
	v_pk_add_f32 v[114:115], v[144:145], v[150:151]
	v_pk_fma_f32 v[50:51], v[50:51], v[146:147], v[84:85] op_sel_hi:[1,0,1]
	v_pk_fma_f32 v[52:53], v[52:53], v[146:147], v[114:115] op_sel_hi:[1,0,1]
	v_mov_b32_e32 v114, v122
	v_mov_b32_e32 v115, v123
.LBB0_5357:
	s_or_b64 exec, exec, s[24:25]
	v_add_f32_e32 v84, v94, v96
	v_fma_f32 v84, -v130, v148, v84
	v_cndmask_b32_e32 v89, v135, v84, vcc
	v_add_f32_e32 v84, v91, v92
	v_fma_f32 v84, -v130, v95, v84
	v_cndmask_b32_e64 v85, v135, v84, s[10:11]
	v_add_f32_e32 v84, v86, v88
	v_add_f32_e32 v82, v82, v83
	v_fma_f32 v84, -v130, v90, v84
	v_fma_f32 v82, -v130, v87, v82
	v_max3_f32 v91, v89, s33, v85
	v_cndmask_b32_e64 v84, v135, v84, s[12:13]
	v_cndmask_b32_e64 v82, v135, v82, s[14:15]
	v_max3_f32 v83, v91, v84, v82
	ds_bpermute_b32 v86, v142, v83
	s_waitcnt lgkmcnt(0)
	v_max_f32_e32 v86, v86, v86
	v_max_f32_e32 v83, v83, v86
	ds_bpermute_b32 v86, v143, v83
	s_waitcnt lgkmcnt(0)
	v_max_f32_e32 v86, v86, v86
	v_max_f32_e32 v83, v83, v86
	v_cmp_neq_f32_e32 vcc, s33, v83
	s_and_saveexec_b64 s[10:11], vcc
	s_cbranch_execz .LBB0_5359
	v_max_f32_e32 v83, v83, v83
	v_max_f32_e32 v86, v111, v111
	v_max_f32_e32 v125, v86, v83
	v_sub_f32_e32 v86, v89, v125
	v_mul_f32_e32 v86, 0x3fb8aa3b, v86
	v_exp_f32_e32 v86, v86
	v_sub_f32_e32 v85, v85, v125
	v_mul_f32_e32 v85, 0x3fb8aa3b, v85
	v_sub_f32_e32 v83, v111, v125
	v_add_f32_e32 v87, 0, v86
	v_pk_fma_f32 v[76:77], v[76:77], v[86:87], 0 op_sel_hi:[1,0,0]
	v_pk_fma_f32 v[74:75], v[74:75], v[86:87], 0 op_sel_hi:[1,0,0]
	v_exp_f32_e32 v86, v85
	v_mul_f32_e32 v83, 0x3fb8aa3b, v83
	v_mov_b32_e32 v111, v125
	v_pk_fma_f32 v[66:67], v[66:67], v[86:87], v[74:75] op_sel_hi:[1,0,1]
	v_sub_f32_e32 v74, v84, v125
	v_mul_f32_e32 v74, 0x3fb8aa3b, v74
	v_exp_f32_e32 v74, v74
	v_add_f32_e32 v85, v86, v87
	v_pk_fma_f32 v[68:69], v[68:69], v[86:87], v[76:77] op_sel_hi:[1,0,1]
	v_add_f32_e32 v75, v74, v85
	v_pk_fma_f32 v[66:67], v[70:71], v[74:75], v[66:67] op_sel_hi:[1,0,1]
	v_sub_f32_e32 v70, v82, v125
	v_mul_f32_e32 v70, 0x3fb8aa3b, v70
	v_exp_f32_e32 v70, v70
	v_pk_fma_f32 v[68:69], v[72:73], v[74:75], v[68:69] op_sel_hi:[1,0,1]
	v_add_f32_e32 v71, v70, v75
	ds_bpermute_b32 v72, v142, v71
	v_pk_fma_f32 v[68:69], v[80:81], v[70:71], v[68:69] op_sel_hi:[1,0,1]
	v_pk_fma_f32 v[66:67], v[78:79], v[70:71], v[66:67] op_sel_hi:[1,0,1]
	ds_bpermute_b32 v73, v142, v67
	ds_bpermute_b32 v74, v142, v68
	s_waitcnt lgkmcnt(0)
	v_add_f32_e32 v71, v71, v72
	ds_bpermute_b32 v72, v143, v71
	ds_bpermute_b32 v75, v142, v69
	v_exp_f32_e32 v70, v83
	s_waitcnt lgkmcnt(0)
	v_add_f32_e32 v124, v71, v72
	ds_bpermute_b32 v72, v142, v66
	s_waitcnt lgkmcnt(0)
	v_pk_add_f32 v[68:69], v[68:69], v[74:75]
	ds_bpermute_b32 v74, v143, v68
	ds_bpermute_b32 v75, v143, v69
	v_fmac_f32_e32 v124, v110, v70
	s_waitcnt lgkmcnt(0)
	v_pk_add_f32 v[66:67], v[66:67], v[72:73]
	ds_bpermute_b32 v72, v143, v66
	ds_bpermute_b32 v73, v143, v67
	s_waitcnt lgkmcnt(0)
	v_pk_add_f32 v[68:69], v[68:69], v[74:75]
	v_mov_b32_e32 v110, v124
	v_pk_fma_f32 v[44:45], v[44:45], v[70:71], v[68:69] op_sel_hi:[1,0,1]
	s_waitcnt lgkmcnt(0)
	v_pk_add_f32 v[66:67], v[66:67], v[72:73]
	s_nop 0
	v_pk_fma_f32 v[42:43], v[42:43], v[70:71], v[66:67] op_sel_hi:[1,0,1]

.LBB0_5407:
	v_max_u32_e32 v54, v1, v34
	v_max3_u32 v54, v54, v35, v36
	v_max3_u32 v54, v54, v37, v38
	v_max3_u32 v54, v54, v39, v40
	v_max3_u32 v54, v54, v41, v42
	v_max3_u32 v54, v54, v43, v44
	v_max3_u32 v54, v54, v45, v46
	v_max3_u32 v54, v54, v47, v48
	s_add_i32 s14, s14, -1
	s_cmp_lg_u32 s14, 0
	s_waitcnt lgkmcnt(0)
	s_nop 1
	v_max_u32_dpp v54, v54, v54 quad_perm:[1,0,3,2] row_mask:0xf bank_mask:0xf
	s_nop 1
	v_max_u32_dpp v54, v54, v54 quad_perm:[2,3,0,1] row_mask:0xf bank_mask:0xf
	s_nop 1
	v_max_u32_dpp v54, v54, v54 row_half_mirror row_mask:0xf bank_mask:0xf
	v_cmp_ne_u32_e64 s[6:7], v1, v54
	v_not_b32_e32 v55, v54
	v_bitop3_b32 v56, v54, s41, v54 bitop3:0xc
	v_cndmask_b32_e64 v1, 0, v1, s[6:7]
	v_cmp_ne_u32_e64 s[6:7], v34, v54
	v_lshlrev_b32_e64 v57, v55, 1
	v_bfe_u32 v55, v55, 5, 2
	v_cndmask_b32_e64 v34, 0, v34, s[6:7]
	v_cmp_ne_u32_e64 s[6:7], v35, v54
	v_cmp_eq_u32_e64 s[8:9], 2, v55
	s_nop 0
	v_cndmask_b32_e64 v35, 0, v35, s[6:7]
	v_cmp_ne_u32_e64 s[6:7], v36, v54
	s_nop 1
	v_cndmask_b32_e64 v36, 0, v36, s[6:7]
	v_cmp_ne_u32_e64 s[6:7], v37, v54
	s_nop 1
	v_cndmask_b32_e64 v37, 0, v37, s[6:7]
	v_cmp_ne_u32_e64 s[6:7], v38, v54
	s_nop 1
	v_cndmask_b32_e64 v38, 0, v38, s[6:7]
	v_cmp_ne_u32_e64 s[6:7], v39, v54
	s_nop 1
	v_cndmask_b32_e64 v39, 0, v39, s[6:7]
	v_cmp_ne_u32_e64 s[6:7], v40, v54
	s_nop 1
	v_cndmask_b32_e64 v40, 0, v40, s[6:7]
	v_cmp_ne_u32_e64 s[6:7], v41, v54
	s_nop 1
	v_cndmask_b32_e64 v41, 0, v41, s[6:7]
	v_cmp_ne_u32_e64 s[6:7], v42, v54
	s_nop 1
	v_cndmask_b32_e64 v42, 0, v42, s[6:7]
	v_cmp_ne_u32_e64 s[6:7], v43, v54
	s_nop 1
	v_cndmask_b32_e64 v43, 0, v43, s[6:7]
	v_cmp_ne_u32_e64 s[6:7], v44, v54
	s_nop 1
	v_cndmask_b32_e64 v44, 0, v44, s[6:7]
	v_cmp_ne_u32_e64 s[6:7], v45, v54
	s_nop 1
	v_cndmask_b32_e64 v45, 0, v45, s[6:7]
	v_cmp_ne_u32_e64 s[6:7], v46, v54
	s_nop 1
	v_cndmask_b32_e64 v46, 0, v46, s[6:7]
	v_cmp_ne_u32_e64 s[6:7], v47, v54
	s_nop 1
	v_cndmask_b32_e64 v47, 0, v47, s[6:7]
	v_cmp_ne_u32_e64 s[6:7], v48, v54
	s_nop 1
	v_cndmask_b32_e64 v48, 0, v48, s[6:7]
	v_cmp_ne_u32_e64 s[6:7], 0, v54
	s_nop 1
	v_cndmask_b32_e64 v54, 0, v57, s[6:7]
	v_cmp_gt_u32_e64 s[6:7], 32, v56
	s_nop 1
	v_cndmask_b32_e64 v56, 0, v54, s[6:7]
	v_cmp_eq_u32_e64 s[6:7], 1, v55
	v_or_b32_e32 v49, v56, v49
	v_cndmask_b32_e64 v56, 0, v54, s[8:9]
	v_cndmask_b32_e64 v57, 0, v54, s[6:7]
	v_cmp_eq_u32_e64 s[6:7], 3, v55
	v_or_b32_e32 v53, v56, v53
	v_or_b32_e32 v52, v57, v52
	v_cndmask_b32_e64 v54, 0, v54, s[6:7]
	v_or_b32_e32 v51, v54, v51
	s_cbranch_scc1 .LBB0_5407
	s_add_i32 s12, s5, 0x19000
	s_and_saveexec_b64 s[6:7], vcc
	s_cbranch_execz .LBB0_5410
	s_lshl_b32 s8, s28, 7
	s_add_i32 s8, s12, s8
	v_lshl_add_u32 v1, v93, 4, s8
	ds_write2_b32 v1, v52, v53 offset0:1 offset1:2
	ds_write2_b32 v1, v49, v51 offset1:3
